# P2/P7 K-loops: LDS-DMA stage loads issued before the ds_read fragment loads in each load phase
# speedup vs baseline: 1.0771x; 1.0057x over previous
; #define PG8_STAGE(bufoff, gbase, voff) do { _Pragma("unroll") for (int _i = 0; _i < 2; ++_i) \
;         __builtin_amdgcn_global_load_lds((const unsigned*)((const char*)(gbase) + (voff)[_i]), (PG8_LAS unsigned*)(lds + (bufoff) + ldsw + _i * 8192), 16, 0, 0); } while (0)
; #define PG8_LDA(dst, b, h) do { _Pragma("unroll") for (int m = 0; m < 4; ++m) _Pragma("unroll") for (int k = 0; k < 2; ++k) dst[m][k] = *(const PG8_LAS bf16x8*)(lds + PG8_SA(b, h) + aoff + m * 2048 + k * 1024); } while (0)
; #define PG8_LDB(dst, b, h) do { _Pragma("unroll") for (int n = 0; n < 2; ++n) _Pragma("unroll") for (int k = 0; k < 2; ++k) dst[n][k] = *(const PG8_LAS bf16x8*)(lds + PG8_SB(b, h) + boff + n * 2048 + k * 1024); } while (0)
; #define PG8_MMA(ai, bj, At, Bt) do { __builtin_amdgcn_s_setprio(1); _Pragma("unroll") for (int m = 0; m < 4; ++m) _Pragma("unroll") for (int n = 0; n < 2; ++n) _Pragma("unroll") for (int k = 0; k < 2; ++k) \
;         acc[ai][bj][m][n] = __builtin_amdgcn_mfma_f32_16x16x32_bf16(Bt[n][k], At[m][k], acc[ai][bj][m][n], 0, 0, 0); __builtin_amdgcn_s_setprio(0); } while (0)
; #define PG8_WAIT_V(n) asm volatile("s_waitcnt vmcnt(" #n ")" ::: "memory")
; #define PG8_WAIT_L(n) asm volatile("s_waitcnt lgkmcnt(" #n ")" ::: "memory")
; #define PG8_BAR __builtin_amdgcn_s_barrier()
; #define PG8_SCHED __builtin_amdgcn_sched_barrier(0)
; template <class Epi, class Sched, bool ALIGN_EPI = false, bool SP2 = false>
; __device__ __forceinline__ void gemm_phase(PG8_LAS unsigned char* lds, const Gemm g, const Sched& S, const Epi& E) {
;     ...
;             PG8_LDB(B0, 0, 0); PG8_LDB(B1, 0, 1); PG8_SCHED; PG8_LDA(At, 0, 0); PG8_STAGE(PG8_SA(1, 1), a1 + hstepA, voffA);
;             PG8_WAIT_V(8); PG8_WAIT_L(0); PG8_BAR; PG8_MMA(0, 0, At, B0); PG8_MMA(0, 1, At, B1); PG8_BAR; PG8_SCHED;
;             PG8_LDA(At, 0, 1); PG8_STAGE(PG8_SB(0, 0), b2, voffB); PG8_STAGE(PG8_SB(0, 1), b2 + hstepB, voffB); PG8_STAGE(PG8_SA(0, 0), a2, voffA);
;             PG8_WAIT_V(8); PG8_WAIT_L(0); PG8_BAR; PG8_MMA(1, 0, At, B0); PG8_MMA(1, 1, At, B1); PG8_BAR; PG8_SCHED;
.LBB0_197:
	s_waitcnt lgkmcnt(0)
	s_add_u32 s66, s60, 0xfffc0080
	s_addc_u32 s67, s61, -1
	s_cmp_eq_u32 s74, 12
	s_cselect_b32 s85, s15, s67
	s_cselect_b32 s84, vcc_lo, s66
	s_cselect_b32 s67, s13, s81
	s_cselect_b32 s66, vcc_hi, s80
	v_lshl_add_u64 v[224:225], s[60:61], 0, v[138:139]
	s_add_i32 m0, s59, 0xc000
	global_load_lds_dwordx4 v[224:225], off
	v_lshl_add_u64 v[224:225], s[60:61], 0, v[140:141]
	s_add_i32 m0, s59, 0xe000
	s_nop 0
	global_load_lds_dwordx4 v[224:225], off
	ds_read_b128 v[146:149], v159
	ds_read_b128 v[162:165], v159 offset:1024
	ds_read_b128 v[166:169], v159 offset:2048
	ds_read_b128 v[170:173], v159 offset:3072
	ds_read_b128 v[176:179], v160
	ds_read_b128 v[180:183], v160 offset:1024
	ds_read_b128 v[184:187], v160 offset:2048
	ds_read_b128 v[188:191], v160 offset:3072
	ds_read_b128 v[192:195], v161
	ds_read_b128 v[196:199], v161 offset:1024
	ds_read_b128 v[200:203], v161 offset:2048
	ds_read_b128 v[204:207], v161 offset:3072
	ds_read_b128 v[208:211], v161 offset:4096
	ds_read_b128 v[212:215], v161 offset:5120
	ds_read_b128 v[216:219], v161 offset:6144
	ds_read_b128 v[220:223], v161 offset:7168
	s_waitcnt vmcnt(8)
	s_waitcnt lgkmcnt(0)
	s_barrier
	s_setprio 1
	s_waitcnt lgkmcnt(0)
	v_mfma_f32_16x16x32_bf16 v[124:127], v[146:149], v[192:195], v[124:127]
	v_mfma_f32_16x16x32_bf16 v[120:123], v[166:169], v[192:195], v[120:123]
	v_mfma_f32_16x16x32_bf16 v[116:119], v[146:149], v[200:203], v[116:119]
	v_mfma_f32_16x16x32_bf16 v[112:115], v[166:169], v[200:203], v[112:115]
	v_mfma_f32_16x16x32_bf16 v[108:111], v[146:149], v[208:211], v[108:111]
	v_mfma_f32_16x16x32_bf16 v[104:107], v[166:169], v[208:211], v[104:107]
	v_mfma_f32_16x16x32_bf16 v[100:103], v[146:149], v[216:219], v[100:103]
	v_mfma_f32_16x16x32_bf16 v[96:99], v[166:169], v[216:219], v[96:99]
	v_mfma_f32_16x16x32_bf16 v[124:127], v[162:165], v[196:199], v[124:127]
	v_mfma_f32_16x16x32_bf16 v[120:123], v[170:173], v[196:199], v[120:123]
	v_mfma_f32_16x16x32_bf16 v[116:119], v[162:165], v[204:207], v[116:119]
	v_mfma_f32_16x16x32_bf16 v[112:115], v[170:173], v[204:207], v[112:115]
	v_mfma_f32_16x16x32_bf16 v[108:111], v[162:165], v[212:215], v[108:111]
	v_mfma_f32_16x16x32_bf16 v[104:107], v[170:173], v[212:215], v[104:107]
	v_mfma_f32_16x16x32_bf16 v[100:103], v[162:165], v[220:223], v[100:103]
	v_mfma_f32_16x16x32_bf16 v[96:99], v[170:173], v[220:223], v[96:99]
	s_setprio 0
	s_setprio 1
	v_mfma_f32_16x16x32_bf16 v[68:71], v[176:179], v[192:195], v[68:71]
	v_mfma_f32_16x16x32_bf16 v[64:67], v[184:187], v[192:195], v[64:67]
	v_mfma_f32_16x16x32_bf16 v[56:59], v[176:179], v[200:203], v[56:59]
	v_mfma_f32_16x16x32_bf16 v[48:51], v[184:187], v[200:203], v[48:51]
	v_mfma_f32_16x16x32_bf16 v[44:47], v[176:179], v[208:211], v[44:47]
	v_mfma_f32_16x16x32_bf16 v[40:43], v[184:187], v[208:211], v[40:43]
	v_mfma_f32_16x16x32_bf16 v[36:39], v[176:179], v[216:219], v[36:39]
	v_mfma_f32_16x16x32_bf16 v[32:35], v[184:187], v[216:219], v[32:35]
	v_mfma_f32_16x16x32_bf16 v[68:71], v[180:183], v[196:199], v[68:71]
	v_mfma_f32_16x16x32_bf16 v[64:67], v[188:191], v[196:199], v[64:67]
	v_mfma_f32_16x16x32_bf16 v[56:59], v[180:183], v[204:207], v[56:59]
	v_mfma_f32_16x16x32_bf16 v[48:51], v[188:191], v[204:207], v[48:51]
	v_mfma_f32_16x16x32_bf16 v[44:47], v[180:183], v[212:215], v[44:47]
	v_mfma_f32_16x16x32_bf16 v[40:43], v[188:191], v[212:215], v[40:43]
	v_mfma_f32_16x16x32_bf16 v[36:39], v[180:183], v[220:223], v[36:39]
	v_mfma_f32_16x16x32_bf16 v[32:35], v[188:191], v[220:223], v[32:35]
	s_setprio 0
	s_barrier
	s_add_i32 s75, s38, s27
	v_lshl_add_u64 v[224:225], s[66:67], 0, v[132:133]
	s_mov_b32 m0, s75
	global_load_lds_dwordx4 v[224:225], off
	s_add_i32 m0, s75, 0x2000
	s_add_u32 s76, s66, 0x40000
	v_lshl_add_u64 v[226:227], s[66:67], 0, v[128:129]
	s_addc_u32 s77, s67, 0
	s_add_i32 s75, s39, s27
	global_load_lds_dwordx4 v[226:227], off
	v_lshl_add_u64 v[228:229], s[76:77], 0, v[132:133]
	s_mov_b32 m0, s75
	v_lshl_add_u64 v[230:231], s[84:85], 0, v[130:131]
	global_load_lds_dwordx4 v[228:229], off
	v_lshl_add_u64 v[228:229], s[76:77], 0, v[128:129]
	s_add_i32 m0, s75, 0x2000
	s_nop 0
	global_load_lds_dwordx4 v[228:229], off
	v_lshl_add_u64 v[228:229], s[84:85], 0, v[134:135]
	s_mov_b32 m0, s59
	s_nop 0
	global_load_lds_dwordx4 v[228:229], off
	s_mov_b32 m0, s86
	s_nop 0
	global_load_lds_dwordx4 v[230:231], off
	ds_read_b128 v[192:195], v161 offset:16384
	ds_read_b128 v[196:199], v161 offset:17408
	ds_read_b128 v[200:203], v161 offset:18432
	ds_read_b128 v[204:207], v161 offset:19456
	ds_read_b128 v[208:211], v161 offset:20480
	ds_read_b128 v[212:215], v161 offset:21504
	ds_read_b128 v[216:219], v161 offset:22528
	ds_read_b128 v[220:223], v161 offset:23552
	s_waitcnt vmcnt(8)
	s_waitcnt lgkmcnt(0)
	s_barrier
; #define PG8_STAGE(bufoff, gbase, voff) do { _Pragma("unroll") for (int _i = 0; _i < 2; ++_i) \
;         __builtin_amdgcn_global_load_lds((const unsigned*)((const char*)(gbase) + (voff)[_i]), (PG8_LAS unsigned*)(lds + (bufoff) + ldsw + _i * 8192), 16, 0, 0); } while (0)
; #define PG8_LDA(dst, b, h) do { _Pragma("unroll") for (int m = 0; m < 4; ++m) _Pragma("unroll") for (int k = 0; k < 2; ++k) dst[m][k] = *(const PG8_LAS bf16x8*)(lds + PG8_SA(b, h) + aoff + m * 2048 + k * 1024); } while (0)
; #define PG8_LDB(dst, b, h) do { _Pragma("unroll") for (int n = 0; n < 2; ++n) _Pragma("unroll") for (int k = 0; k < 2; ++k) dst[n][k] = *(const PG8_LAS bf16x8*)(lds + PG8_SB(b, h) + boff + n * 2048 + k * 1024); } while (0)
; #define PG8_MMA(ai, bj, At, Bt) do { __builtin_amdgcn_s_setprio(1); _Pragma("unroll") for (int m = 0; m < 4; ++m) _Pragma("unroll") for (int n = 0; n < 2; ++n) _Pragma("unroll") for (int k = 0; k < 2; ++k) \
;         acc[ai][bj][m][n] = __builtin_amdgcn_mfma_f32_16x16x32_bf16(Bt[n][k], At[m][k], acc[ai][bj][m][n], 0, 0, 0); __builtin_amdgcn_s_setprio(0); } while (0)
; #define PG8_WAIT_V(n) asm volatile("s_waitcnt vmcnt(" #n ")" ::: "memory")
; #define PG8_WAIT_L(n) asm volatile("s_waitcnt lgkmcnt(" #n ")" ::: "memory")
; #define PG8_BAR __builtin_amdgcn_s_barrier()
; #define PG8_SCHED __builtin_amdgcn_sched_barrier(0)
; template <class Epi, class Sched, bool ALIGN_EPI = false, bool SP2 = false>
; __device__ __forceinline__ void gemm_phase(PG8_LAS unsigned char* lds, const Gemm g, const Sched& S, const Epi& E) {
;     ...
;             PG8_WAIT_V(8); PG8_WAIT_L(0); PG8_BAR; PG8_MMA(1, 0, At, B0); PG8_MMA(1, 1, At, B1); PG8_BAR; PG8_SCHED;
;             PG8_LDB(B0, 1, 0); PG8_LDB(B1, 1, 1); PG8_SCHED; PG8_LDA(At, 1, 0); PG8_STAGE(PG8_SA(0, 1), a2 + hstepA, voffA);
;             PG8_WAIT_V(8); PG8_WAIT_L(0); PG8_BAR; PG8_MMA(0, 0, At, B0); PG8_MMA(0, 1, At, B1); PG8_BAR; PG8_SCHED;
	s_setprio 1
	s_waitcnt lgkmcnt(0)
	v_mfma_f32_16x16x32_bf16 v[92:95], v[146:149], v[192:195], v[92:95]
	v_mfma_f32_16x16x32_bf16 v[88:91], v[166:169], v[192:195], v[88:91]
	v_mfma_f32_16x16x32_bf16 v[84:87], v[146:149], v[200:203], v[84:87]
	v_mfma_f32_16x16x32_bf16 v[80:83], v[166:169], v[200:203], v[80:83]
	v_mfma_f32_16x16x32_bf16 v[76:79], v[146:149], v[208:211], v[76:79]
	v_mfma_f32_16x16x32_bf16 v[72:75], v[166:169], v[208:211], v[72:75]
	v_mfma_f32_16x16x32_bf16 v[60:63], v[146:149], v[216:219], v[60:63]
	v_mfma_f32_16x16x32_bf16 v[52:55], v[166:169], v[216:219], v[52:55]
	v_mfma_f32_16x16x32_bf16 v[92:95], v[162:165], v[196:199], v[92:95]
	v_mfma_f32_16x16x32_bf16 v[88:91], v[170:173], v[196:199], v[88:91]
	v_mfma_f32_16x16x32_bf16 v[84:87], v[162:165], v[204:207], v[84:87]
	v_mfma_f32_16x16x32_bf16 v[80:83], v[170:173], v[204:207], v[80:83]
	v_mfma_f32_16x16x32_bf16 v[76:79], v[162:165], v[212:215], v[76:79]
	v_mfma_f32_16x16x32_bf16 v[72:75], v[170:173], v[212:215], v[72:75]
	v_mfma_f32_16x16x32_bf16 v[60:63], v[162:165], v[220:223], v[60:63]
	v_mfma_f32_16x16x32_bf16 v[52:55], v[170:173], v[220:223], v[52:55]
	s_setprio 0
	s_setprio 1
	v_mfma_f32_16x16x32_bf16 v[28:31], v[176:179], v[192:195], v[28:31]
	v_mfma_f32_16x16x32_bf16 v[24:27], v[184:187], v[192:195], v[24:27]
	v_mfma_f32_16x16x32_bf16 v[20:23], v[176:179], v[200:203], v[20:23]
	v_mfma_f32_16x16x32_bf16 v[16:19], v[184:187], v[200:203], v[16:19]
	v_mfma_f32_16x16x32_bf16 v[12:15], v[176:179], v[208:211], v[12:15]
	v_mfma_f32_16x16x32_bf16 v[8:11], v[184:187], v[208:211], v[8:11]
	v_mfma_f32_16x16x32_bf16 v[4:7], v[176:179], v[216:219], v[4:7]
	v_mfma_f32_16x16x32_bf16 v[0:3], v[184:187], v[216:219], v[0:3]
	v_mfma_f32_16x16x32_bf16 v[28:31], v[180:183], v[196:199], v[28:31]
	v_mfma_f32_16x16x32_bf16 v[24:27], v[188:191], v[196:199], v[24:27]
	v_mfma_f32_16x16x32_bf16 v[20:23], v[180:183], v[204:207], v[20:23]
	v_mfma_f32_16x16x32_bf16 v[16:19], v[188:191], v[204:207], v[16:19]
	v_mfma_f32_16x16x32_bf16 v[12:15], v[180:183], v[212:215], v[12:15]
	v_mfma_f32_16x16x32_bf16 v[8:11], v[188:191], v[212:215], v[8:11]
	v_mfma_f32_16x16x32_bf16 v[4:7], v[180:183], v[220:223], v[4:7]
	v_mfma_f32_16x16x32_bf16 v[0:3], v[188:191], v[220:223], v[0:3]
	s_setprio 0
	s_barrier
	s_add_i32 s75, 0, 0x18000
	s_add_i32 s33, 0, 0x1c000
	v_add_u32_e32 v170, s75, v151
	v_add_u32_e32 v175, s33, v151
	s_add_u32 s76, s84, 0x40000
	s_addc_u32 s77, s85, 0
	s_mov_b32 m0, s87
	v_lshl_add_u64 v[232:233], s[76:77], 0, v[134:135]
	global_load_lds_dwordx4 v[232:233], off
	v_lshl_add_u64 v[232:233], s[76:77], 0, v[130:131]
	s_mov_b32 m0, s88
	s_nop 0
	global_load_lds_dwordx4 v[232:233], off
	ds_read_b128 v[146:149], v170
	ds_read_b128 v[162:165], v170 offset:1024
	ds_read_b128 v[166:169], v170 offset:2048
	ds_read_b128 v[170:173], v170 offset:3072
	ds_read_b128 v[176:179], v175
	ds_read_b128 v[180:183], v175 offset:1024
	ds_read_b128 v[184:187], v175 offset:2048
	ds_read_b128 v[188:191], v175 offset:3072
	ds_read_b128 v[192:195], v161 offset:32768
	ds_read_b128 v[196:199], v161 offset:33792
	ds_read_b128 v[200:203], v161 offset:34816
	ds_read_b128 v[204:207], v161 offset:35840
	ds_read_b128 v[208:211], v161 offset:36864
	ds_read_b128 v[212:215], v161 offset:37888
	ds_read_b128 v[216:219], v161 offset:38912
	ds_read_b128 v[220:223], v161 offset:39936
	s_waitcnt vmcnt(8)
	s_waitcnt lgkmcnt(0)
	s_barrier
	s_setprio 1
	s_waitcnt lgkmcnt(0)
	v_mfma_f32_16x16x32_bf16 v[124:127], v[146:149], v[192:195], v[124:127]
	v_mfma_f32_16x16x32_bf16 v[120:123], v[166:169], v[192:195], v[120:123]
	v_mfma_f32_16x16x32_bf16 v[116:119], v[146:149], v[200:203], v[116:119]
	v_mfma_f32_16x16x32_bf16 v[112:115], v[166:169], v[200:203], v[112:115]
	v_mfma_f32_16x16x32_bf16 v[108:111], v[146:149], v[208:211], v[108:111]
	v_mfma_f32_16x16x32_bf16 v[104:107], v[166:169], v[208:211], v[104:107]
	v_mfma_f32_16x16x32_bf16 v[100:103], v[146:149], v[216:219], v[100:103]
	v_mfma_f32_16x16x32_bf16 v[96:99], v[166:169], v[216:219], v[96:99]
	v_mfma_f32_16x16x32_bf16 v[124:127], v[162:165], v[196:199], v[124:127]
	v_mfma_f32_16x16x32_bf16 v[120:123], v[170:173], v[196:199], v[120:123]
	v_mfma_f32_16x16x32_bf16 v[116:119], v[162:165], v[204:207], v[116:119]
	v_mfma_f32_16x16x32_bf16 v[112:115], v[170:173], v[204:207], v[112:115]
	v_mfma_f32_16x16x32_bf16 v[108:111], v[162:165], v[212:215], v[108:111]
	v_mfma_f32_16x16x32_bf16 v[104:107], v[170:173], v[212:215], v[104:107]
	v_mfma_f32_16x16x32_bf16 v[100:103], v[162:165], v[220:223], v[100:103]
	v_mfma_f32_16x16x32_bf16 v[96:99], v[170:173], v[220:223], v[96:99]
	s_setprio 0
	s_setprio 1
	v_mfma_f32_16x16x32_bf16 v[68:71], v[176:179], v[192:195], v[68:71]
	v_mfma_f32_16x16x32_bf16 v[64:67], v[184:187], v[192:195], v[64:67]
	v_mfma_f32_16x16x32_bf16 v[56:59], v[176:179], v[200:203], v[56:59]
	v_mfma_f32_16x16x32_bf16 v[48:51], v[184:187], v[200:203], v[48:51]
	v_mfma_f32_16x16x32_bf16 v[44:47], v[176:179], v[208:211], v[44:47]
	v_mfma_f32_16x16x32_bf16 v[40:43], v[184:187], v[208:211], v[40:43]
	v_mfma_f32_16x16x32_bf16 v[36:39], v[176:179], v[216:219], v[36:39]
	v_mfma_f32_16x16x32_bf16 v[32:35], v[184:187], v[216:219], v[32:35]
	v_mfma_f32_16x16x32_bf16 v[68:71], v[180:183], v[196:199], v[68:71]
	v_mfma_f32_16x16x32_bf16 v[64:67], v[188:191], v[196:199], v[64:67]
	v_mfma_f32_16x16x32_bf16 v[56:59], v[180:183], v[204:207], v[56:59]
	v_mfma_f32_16x16x32_bf16 v[48:51], v[188:191], v[204:207], v[48:51]
	v_mfma_f32_16x16x32_bf16 v[44:47], v[180:183], v[212:215], v[44:47]
	v_mfma_f32_16x16x32_bf16 v[40:43], v[188:191], v[212:215], v[40:43]
	v_mfma_f32_16x16x32_bf16 v[36:39], v[180:183], v[220:223], v[36:39]
	v_mfma_f32_16x16x32_bf16 v[32:35], v[188:191], v[220:223], v[32:35]
	s_setprio 0
	s_barrier
; #define PG8_STAGE(bufoff, gbase, voff) do { _Pragma("unroll") for (int _i = 0; _i < 2; ++_i) \
;         __builtin_amdgcn_global_load_lds((const unsigned*)((const char*)(gbase) + (voff)[_i]), (PG8_LAS unsigned*)(lds + (bufoff) + ldsw + _i * 8192), 16, 0, 0); } while (0)
; #define PG8_LDA(dst, b, h) do { _Pragma("unroll") for (int m = 0; m < 4; ++m) _Pragma("unroll") for (int k = 0; k < 2; ++k) dst[m][k] = *(const PG8_LAS bf16x8*)(lds + PG8_SA(b, h) + aoff + m * 2048 + k * 1024); } while (0)
; #define PG8_MMA(ai, bj, At, Bt) do { __builtin_amdgcn_s_setprio(1); _Pragma("unroll") for (int m = 0; m < 4; ++m) _Pragma("unroll") for (int n = 0; n < 2; ++n) _Pragma("unroll") for (int k = 0; k < 2; ++k) \
;         acc[ai][bj][m][n] = __builtin_amdgcn_mfma_f32_16x16x32_bf16(Bt[n][k], At[m][k], acc[ai][bj][m][n], 0, 0, 0); __builtin_amdgcn_s_setprio(0); } while (0)
; #define PG8_WAIT_V(n) asm volatile("s_waitcnt vmcnt(" #n ")" ::: "memory")
; #define PG8_WAIT_L(n) asm volatile("s_waitcnt lgkmcnt(" #n ")" ::: "memory")
; #define PG8_BAR __builtin_amdgcn_s_barrier()
; #define PG8_SCHED __builtin_amdgcn_sched_barrier(0)
; template <class Epi, class Sched, bool ALIGN_EPI = false, bool SP2 = false>
; __device__ __forceinline__ void gemm_phase(PG8_LAS unsigned char* lds, const Gemm g, const Sched& S, const Epi& E) {
;     ...
;             PG8_LDA(At, 1, 1); PG8_STAGE(PG8_SB(1, 0), b3, voffB); PG8_STAGE(PG8_SB(1, 1), b3 + hstepB, voffB); PG8_STAGE(PG8_SA(1, 0), a3, voffA);
;             PG8_WAIT_V(8); PG8_WAIT_L(0); PG8_BAR; PG8_MMA(1, 0, At, B0); PG8_MMA(1, 1, At, B1); PG8_BAR; PG8_SCHED;
	s_add_i32 s75, s75, s27
	v_lshl_add_u64 v[224:225], v[224:225], 0, s[8:9]
	s_mov_b32 m0, s75
	global_load_lds_dwordx4 v[224:225], off
	s_add_i32 m0, s75, 0x2000
	s_add_u32 s66, s66, 0x40080
	v_lshl_add_u64 v[224:225], v[226:227], 0, s[8:9]
	s_addc_u32 s67, s67, 0
	s_add_i32 s33, s33, s27
	global_load_lds_dwordx4 v[224:225], off
	v_lshl_add_u64 v[224:225], s[66:67], 0, v[132:133]
	s_mov_b32 m0, s33
	s_nop 0
	global_load_lds_dwordx4 v[224:225], off
	v_lshl_add_u64 v[224:225], s[66:67], 0, v[128:129]
	s_add_i32 m0, s33, 0x2000
	s_nop 0
	global_load_lds_dwordx4 v[224:225], off
	v_lshl_add_u64 v[224:225], v[228:229], 0, s[8:9]
	s_mov_b32 m0, s91
	s_nop 0
	global_load_lds_dwordx4 v[224:225], off
	v_lshl_add_u64 v[224:225], v[230:231], 0, s[8:9]
	s_mov_b32 m0, s92
	s_nop 0
	global_load_lds_dwordx4 v[224:225], off
	ds_read_b128 v[192:195], v161 offset:49152
	ds_read_b128 v[196:199], v161 offset:50176
	ds_read_b128 v[200:203], v161 offset:51200
	ds_read_b128 v[204:207], v161 offset:52224
	ds_read_b128 v[208:211], v161 offset:53248
	ds_read_b128 v[212:215], v161 offset:54272
	ds_read_b128 v[216:219], v161 offset:55296
	ds_read_b128 v[220:223], v161 offset:56320
	s_waitcnt vmcnt(8)
	s_waitcnt lgkmcnt(0)
	s_barrier
	s_setprio 1
	s_waitcnt lgkmcnt(0)
	v_mfma_f32_16x16x32_bf16 v[92:95], v[146:149], v[192:195], v[92:95]
	v_mfma_f32_16x16x32_bf16 v[88:91], v[166:169], v[192:195], v[88:91]
	v_mfma_f32_16x16x32_bf16 v[84:87], v[146:149], v[200:203], v[84:87]
	v_mfma_f32_16x16x32_bf16 v[80:83], v[166:169], v[200:203], v[80:83]
	v_mfma_f32_16x16x32_bf16 v[76:79], v[146:149], v[208:211], v[76:79]
	v_mfma_f32_16x16x32_bf16 v[72:75], v[166:169], v[208:211], v[72:75]
	v_mfma_f32_16x16x32_bf16 v[60:63], v[146:149], v[216:219], v[60:63]
	v_mfma_f32_16x16x32_bf16 v[52:55], v[166:169], v[216:219], v[52:55]
	v_mfma_f32_16x16x32_bf16 v[92:95], v[162:165], v[196:199], v[92:95]
	v_mfma_f32_16x16x32_bf16 v[88:91], v[170:173], v[196:199], v[88:91]
	v_mfma_f32_16x16x32_bf16 v[84:87], v[162:165], v[204:207], v[84:87]
	v_mfma_f32_16x16x32_bf16 v[80:83], v[170:173], v[204:207], v[80:83]
	v_mfma_f32_16x16x32_bf16 v[76:79], v[162:165], v[212:215], v[76:79]
	v_mfma_f32_16x16x32_bf16 v[72:75], v[170:173], v[212:215], v[72:75]
	v_mfma_f32_16x16x32_bf16 v[60:63], v[162:165], v[220:223], v[60:63]
	v_mfma_f32_16x16x32_bf16 v[52:55], v[170:173], v[220:223], v[52:55]
	s_setprio 0
	s_setprio 1
	v_mfma_f32_16x16x32_bf16 v[28:31], v[176:179], v[192:195], v[28:31]
	v_mfma_f32_16x16x32_bf16 v[24:27], v[184:187], v[192:195], v[24:27]
	v_mfma_f32_16x16x32_bf16 v[20:23], v[176:179], v[200:203], v[20:23]
	v_mfma_f32_16x16x32_bf16 v[16:19], v[184:187], v[200:203], v[16:19]
	v_mfma_f32_16x16x32_bf16 v[12:15], v[176:179], v[208:211], v[12:15]
	v_mfma_f32_16x16x32_bf16 v[8:11], v[184:187], v[208:211], v[8:11]
	v_mfma_f32_16x16x32_bf16 v[4:7], v[176:179], v[216:219], v[4:7]
	v_mfma_f32_16x16x32_bf16 v[0:3], v[184:187], v[216:219], v[0:3]
	v_mfma_f32_16x16x32_bf16 v[28:31], v[180:183], v[196:199], v[28:31]
	v_mfma_f32_16x16x32_bf16 v[24:27], v[188:191], v[196:199], v[24:27]
	v_mfma_f32_16x16x32_bf16 v[20:23], v[180:183], v[204:207], v[20:23]
	v_mfma_f32_16x16x32_bf16 v[16:19], v[188:191], v[204:207], v[16:19]
	v_mfma_f32_16x16x32_bf16 v[12:15], v[180:183], v[212:215], v[12:15]
	v_mfma_f32_16x16x32_bf16 v[8:11], v[188:191], v[212:215], v[8:11]
	v_mfma_f32_16x16x32_bf16 v[4:7], v[180:183], v[220:223], v[4:7]
	v_mfma_f32_16x16x32_bf16 v[0:3], v[188:191], v[220:223], v[0:3]
	s_setprio 0
	s_barrier
	s_add_i32 s74, s74, 2
	s_add_u32 s60, s60, 0x100
	s_addc_u32 s61, s61, 0
	s_add_u32 s80, s80, 0x100
	s_addc_u32 s81, s81, 0
	s_cmp_gt_u32 s74, 13
	s_cbranch_scc0 .LBB0_197
	s_add_u32 s100, vcc_lo, 0x40080
	s_addc_u32 s101, s15, 0
	s_and_b64 vcc, exec, s[10:11]
	s_cbranch_vccnz .LBB0_203
	v_lshl_add_u64 v[224:225], s[100:101], 0, v[138:139]
	s_add_i32 m0, s59, 0xc000
	v_lshl_add_u64 v[226:227], s[100:101], 0, v[140:141]
	global_load_lds_dwordx4 v[224:225], off
	s_add_i32 m0, s59, 0xe000
	s_nop 0
	global_load_lds_dwordx4 v[226:227], off
	s_and_b32 s13, s73, -4
	s_cmp_lg_u32 s13, 4
	s_cbranch_scc0 .LBB0_204

; #define PG8_STAGE(bufoff, gbase, voff) do { _Pragma("unroll") for (int _i = 0; _i < 2; ++_i) \
;         __builtin_amdgcn_global_load_lds((const unsigned*)((const char*)(gbase) + (voff)[_i]), (PG8_LAS unsigned*)(lds + (bufoff) + ldsw + _i * 8192), 16, 0, 0); } while (0)
; #define PG8_LDA(dst, b, h) do { _Pragma("unroll") for (int m = 0; m < 4; ++m) _Pragma("unroll") for (int k = 0; k < 2; ++k) dst[m][k] = *(const PG8_LAS bf16x8*)(lds + PG8_SA(b, h) + aoff + m * 2048 + k * 1024); } while (0)
; #define PG8_LDB(dst, b, h) do { _Pragma("unroll") for (int n = 0; n < 2; ++n) _Pragma("unroll") for (int k = 0; k < 2; ++k) dst[n][k] = *(const PG8_LAS bf16x8*)(lds + PG8_SB(b, h) + boff + n * 2048 + k * 1024); } while (0)
; #define PG8_MMA(ai, bj, At, Bt) do { __builtin_amdgcn_s_setprio(1); _Pragma("unroll") for (int m = 0; m < 4; ++m) _Pragma("unroll") for (int n = 0; n < 2; ++n) _Pragma("unroll") for (int k = 0; k < 2; ++k) \
;         acc[ai][bj][m][n] = __builtin_amdgcn_mfma_f32_16x16x32_bf16(Bt[n][k], At[m][k], acc[ai][bj][m][n], 0, 0, 0); __builtin_amdgcn_s_setprio(0); } while (0)
; #define PG8_WAIT_V(n) asm volatile("s_waitcnt vmcnt(" #n ")" ::: "memory")
; #define PG8_WAIT_L(n) asm volatile("s_waitcnt lgkmcnt(" #n ")" ::: "memory")
; #define PG8_BAR __builtin_amdgcn_s_barrier()
; #define PG8_SCHED __builtin_amdgcn_sched_barrier(0)
; template <class Epi, class Sched, bool ALIGN_EPI = false, bool SP2 = false>
; __device__ __forceinline__ void gemm_phase(PG8_LAS unsigned char* lds, const Gemm g, const Sched& S, const Epi& E) {
;     ...
;             PG8_LDB(B0, 0, 0); PG8_LDB(B1, 0, 1); PG8_SCHED; PG8_LDA(At, 0, 0); PG8_STAGE(PG8_SA(1, 1), a1 + hstepA, voffA);
;             PG8_WAIT_V(8); PG8_WAIT_L(0); PG8_BAR; PG8_MMA(0, 0, At, B0); PG8_MMA(0, 1, At, B1); PG8_BAR; PG8_SCHED;
;             PG8_LDA(At, 0, 1); PG8_STAGE(PG8_SB(0, 0), b2, voffB); PG8_STAGE(PG8_SB(0, 1), b2 + hstepB, voffB); PG8_STAGE(PG8_SA(0, 0), a2, voffA);
;             PG8_WAIT_V(8); PG8_WAIT_L(0); PG8_BAR; PG8_MMA(1, 0, At, B0); PG8_MMA(1, 1, At, B1); PG8_BAR; PG8_SCHED;
;     ...
;                     for (int n = 0; n < 2; ++n) acc[a][b][m][n] = (f32x4){0.f, 0.f, 0.f, 0.f};
.Lpeel_p2:
	s_waitcnt lgkmcnt(0)
	ds_read_b128 v[146:149], v159
	ds_read_b128 v[162:165], v159 offset:1024
	ds_read_b128 v[166:169], v159 offset:2048
	ds_read_b128 v[170:173], v159 offset:3072
	ds_read_b128 v[176:179], v160
	ds_read_b128 v[180:183], v160 offset:1024
	ds_read_b128 v[184:187], v160 offset:2048
	ds_read_b128 v[188:191], v160 offset:3072
	s_add_u32 s66, s60, 0xfffc0080
	s_addc_u32 s67, s61, -1
	s_cmp_eq_u32 s74, 12
	s_cselect_b32 s85, s15, s67
	s_cselect_b32 s84, vcc_lo, s66
	s_cselect_b32 s67, s13, s81
	s_cselect_b32 s66, vcc_hi, s80
	ds_read_b128 v[192:195], v161
	ds_read_b128 v[196:199], v161 offset:1024
	ds_read_b128 v[200:203], v161 offset:2048
	ds_read_b128 v[204:207], v161 offset:3072
	ds_read_b128 v[208:211], v161 offset:4096
	ds_read_b128 v[212:215], v161 offset:5120
	ds_read_b128 v[216:219], v161 offset:6144
	ds_read_b128 v[220:223], v161 offset:7168
	s_waitcnt vmcnt(24)
	s_waitcnt lgkmcnt(0)
	s_barrier
	s_setprio 1
	s_waitcnt lgkmcnt(0)
	v_mfma_f32_16x16x32_bf16 v[124:127], v[146:149], v[192:195], 0
	v_mfma_f32_16x16x32_bf16 v[120:123], v[166:169], v[192:195], 0
	v_mfma_f32_16x16x32_bf16 v[116:119], v[146:149], v[200:203], 0
	v_mfma_f32_16x16x32_bf16 v[112:115], v[166:169], v[200:203], 0
	v_mfma_f32_16x16x32_bf16 v[108:111], v[146:149], v[208:211], 0
	v_mfma_f32_16x16x32_bf16 v[104:107], v[166:169], v[208:211], 0
	v_mfma_f32_16x16x32_bf16 v[100:103], v[146:149], v[216:219], 0
	v_mfma_f32_16x16x32_bf16 v[96:99], v[166:169], v[216:219], 0
	v_mfma_f32_16x16x32_bf16 v[124:127], v[162:165], v[196:199], v[124:127]
	v_mfma_f32_16x16x32_bf16 v[120:123], v[170:173], v[196:199], v[120:123]
	v_mfma_f32_16x16x32_bf16 v[116:119], v[162:165], v[204:207], v[116:119]
	v_mfma_f32_16x16x32_bf16 v[112:115], v[170:173], v[204:207], v[112:115]
	v_mfma_f32_16x16x32_bf16 v[108:111], v[162:165], v[212:215], v[108:111]
	v_mfma_f32_16x16x32_bf16 v[104:107], v[170:173], v[212:215], v[104:107]
	v_mfma_f32_16x16x32_bf16 v[100:103], v[162:165], v[220:223], v[100:103]
	v_mfma_f32_16x16x32_bf16 v[96:99], v[170:173], v[220:223], v[96:99]
	s_setprio 0
	s_setprio 1
	v_mfma_f32_16x16x32_bf16 v[68:71], v[176:179], v[192:195], 0
	v_mfma_f32_16x16x32_bf16 v[64:67], v[184:187], v[192:195], 0
	v_mfma_f32_16x16x32_bf16 v[56:59], v[176:179], v[200:203], 0
	v_mfma_f32_16x16x32_bf16 v[48:51], v[184:187], v[200:203], 0
	v_mfma_f32_16x16x32_bf16 v[44:47], v[176:179], v[208:211], 0
	v_mfma_f32_16x16x32_bf16 v[40:43], v[184:187], v[208:211], 0
	v_mfma_f32_16x16x32_bf16 v[36:39], v[176:179], v[216:219], 0
	v_mfma_f32_16x16x32_bf16 v[32:35], v[184:187], v[216:219], 0
	v_mfma_f32_16x16x32_bf16 v[68:71], v[180:183], v[196:199], v[68:71]
	v_mfma_f32_16x16x32_bf16 v[64:67], v[188:191], v[196:199], v[64:67]
	v_mfma_f32_16x16x32_bf16 v[56:59], v[180:183], v[204:207], v[56:59]
	v_mfma_f32_16x16x32_bf16 v[48:51], v[188:191], v[204:207], v[48:51]
	v_mfma_f32_16x16x32_bf16 v[44:47], v[180:183], v[212:215], v[44:47]
	v_mfma_f32_16x16x32_bf16 v[40:43], v[188:191], v[212:215], v[40:43]
	v_mfma_f32_16x16x32_bf16 v[36:39], v[180:183], v[220:223], v[36:39]
	v_mfma_f32_16x16x32_bf16 v[32:35], v[188:191], v[220:223], v[32:35]
	s_setprio 0
	s_barrier
	s_add_i32 s75, s38, s27
	v_lshl_add_u64 v[224:225], s[66:67], 0, v[132:133]
	s_mov_b32 m0, s75
	global_load_lds_dwordx4 v[224:225], off
	s_add_i32 m0, s75, 0x2000
	s_add_u32 s76, s66, 0x40000
	v_lshl_add_u64 v[226:227], s[66:67], 0, v[128:129]
	s_addc_u32 s77, s67, 0
	s_add_i32 s75, s39, s27
	global_load_lds_dwordx4 v[226:227], off
	v_lshl_add_u64 v[228:229], s[76:77], 0, v[132:133]
	s_mov_b32 m0, s75
	v_lshl_add_u64 v[230:231], s[84:85], 0, v[130:131]
	global_load_lds_dwordx4 v[228:229], off
	v_lshl_add_u64 v[228:229], s[76:77], 0, v[128:129]
	s_add_i32 m0, s75, 0x2000
	s_nop 0
	global_load_lds_dwordx4 v[228:229], off
	v_lshl_add_u64 v[228:229], s[84:85], 0, v[134:135]
	s_mov_b32 m0, s59
	s_nop 0
	global_load_lds_dwordx4 v[228:229], off
	s_mov_b32 m0, s86
	s_nop 0
	global_load_lds_dwordx4 v[230:231], off
	ds_read_b128 v[192:195], v161 offset:16384
	ds_read_b128 v[196:199], v161 offset:17408
	ds_read_b128 v[200:203], v161 offset:18432
	ds_read_b128 v[204:207], v161 offset:19456
	ds_read_b128 v[208:211], v161 offset:20480
	ds_read_b128 v[212:215], v161 offset:21504
	ds_read_b128 v[216:219], v161 offset:22528
	ds_read_b128 v[220:223], v161 offset:23552
	s_waitcnt vmcnt(24)
	s_waitcnt lgkmcnt(0)
	s_barrier
	s_setprio 1
	s_waitcnt lgkmcnt(0)
	v_mfma_f32_16x16x32_bf16 v[92:95], v[146:149], v[192:195], 0
	v_mfma_f32_16x16x32_bf16 v[88:91], v[166:169], v[192:195], 0
	v_mfma_f32_16x16x32_bf16 v[84:87], v[146:149], v[200:203], 0
	v_mfma_f32_16x16x32_bf16 v[80:83], v[166:169], v[200:203], 0
	v_mfma_f32_16x16x32_bf16 v[76:79], v[146:149], v[208:211], 0
	v_mfma_f32_16x16x32_bf16 v[72:75], v[166:169], v[208:211], 0
	v_mfma_f32_16x16x32_bf16 v[60:63], v[146:149], v[216:219], 0
	v_mfma_f32_16x16x32_bf16 v[52:55], v[166:169], v[216:219], 0
	v_mfma_f32_16x16x32_bf16 v[92:95], v[162:165], v[196:199], v[92:95]
	v_mfma_f32_16x16x32_bf16 v[88:91], v[170:173], v[196:199], v[88:91]
	v_mfma_f32_16x16x32_bf16 v[84:87], v[162:165], v[204:207], v[84:87]
	v_mfma_f32_16x16x32_bf16 v[80:83], v[170:173], v[204:207], v[80:83]
	v_mfma_f32_16x16x32_bf16 v[76:79], v[162:165], v[212:215], v[76:79]
	v_mfma_f32_16x16x32_bf16 v[72:75], v[170:173], v[212:215], v[72:75]
	v_mfma_f32_16x16x32_bf16 v[60:63], v[162:165], v[220:223], v[60:63]
	v_mfma_f32_16x16x32_bf16 v[52:55], v[170:173], v[220:223], v[52:55]
	s_setprio 0
	s_setprio 1
	v_mfma_f32_16x16x32_bf16 v[28:31], v[176:179], v[192:195], 0
	v_mfma_f32_16x16x32_bf16 v[24:27], v[184:187], v[192:195], 0
	v_mfma_f32_16x16x32_bf16 v[20:23], v[176:179], v[200:203], 0
	v_mfma_f32_16x16x32_bf16 v[16:19], v[184:187], v[200:203], 0
	v_mfma_f32_16x16x32_bf16 v[12:15], v[176:179], v[208:211], 0
	v_mfma_f32_16x16x32_bf16 v[8:11], v[184:187], v[208:211], 0
	v_mfma_f32_16x16x32_bf16 v[4:7], v[176:179], v[216:219], 0
	v_mfma_f32_16x16x32_bf16 v[0:3], v[184:187], v[216:219], 0
	v_mfma_f32_16x16x32_bf16 v[28:31], v[180:183], v[196:199], v[28:31]
	v_mfma_f32_16x16x32_bf16 v[24:27], v[188:191], v[196:199], v[24:27]
	v_mfma_f32_16x16x32_bf16 v[20:23], v[180:183], v[204:207], v[20:23]
	v_mfma_f32_16x16x32_bf16 v[16:19], v[188:191], v[204:207], v[16:19]
	v_mfma_f32_16x16x32_bf16 v[12:15], v[180:183], v[212:215], v[12:15]
	v_mfma_f32_16x16x32_bf16 v[8:11], v[188:191], v[212:215], v[8:11]
	v_mfma_f32_16x16x32_bf16 v[4:7], v[180:183], v[220:223], v[4:7]
	v_mfma_f32_16x16x32_bf16 v[0:3], v[188:191], v[220:223], v[0:3]
	s_setprio 0
	s_barrier
; #define PG8_STAGE(bufoff, gbase, voff) do { _Pragma("unroll") for (int _i = 0; _i < 2; ++_i) \
;         __builtin_amdgcn_global_load_lds((const unsigned*)((const char*)(gbase) + (voff)[_i]), (PG8_LAS unsigned*)(lds + (bufoff) + ldsw + _i * 8192), 16, 0, 0); } while (0)
; #define PG8_LDA(dst, b, h) do { _Pragma("unroll") for (int m = 0; m < 4; ++m) _Pragma("unroll") for (int k = 0; k < 2; ++k) dst[m][k] = *(const PG8_LAS bf16x8*)(lds + PG8_SA(b, h) + aoff + m * 2048 + k * 1024); } while (0)
; #define PG8_LDB(dst, b, h) do { _Pragma("unroll") for (int n = 0; n < 2; ++n) _Pragma("unroll") for (int k = 0; k < 2; ++k) dst[n][k] = *(const PG8_LAS bf16x8*)(lds + PG8_SB(b, h) + boff + n * 2048 + k * 1024); } while (0)
; #define PG8_MMA(ai, bj, At, Bt) do { __builtin_amdgcn_s_setprio(1); _Pragma("unroll") for (int m = 0; m < 4; ++m) _Pragma("unroll") for (int n = 0; n < 2; ++n) _Pragma("unroll") for (int k = 0; k < 2; ++k) \
;         acc[ai][bj][m][n] = __builtin_amdgcn_mfma_f32_16x16x32_bf16(Bt[n][k], At[m][k], acc[ai][bj][m][n], 0, 0, 0); __builtin_amdgcn_s_setprio(0); } while (0)
; #define PG8_WAIT_V(n) asm volatile("s_waitcnt vmcnt(" #n ")" ::: "memory")
; #define PG8_WAIT_L(n) asm volatile("s_waitcnt lgkmcnt(" #n ")" ::: "memory")
; #define PG8_BAR __builtin_amdgcn_s_barrier()
; #define PG8_SCHED __builtin_amdgcn_sched_barrier(0)
; template <class Epi, class Sched, bool ALIGN_EPI = false, bool SP2 = false>
; __device__ __forceinline__ void gemm_phase(PG8_LAS unsigned char* lds, const Gemm g, const Sched& S, const Epi& E) {
;     ...
;             PG8_LDB(B0, 1, 0); PG8_LDB(B1, 1, 1); PG8_SCHED; PG8_LDA(At, 1, 0); PG8_STAGE(PG8_SA(0, 1), a2 + hstepA, voffA);
;             PG8_WAIT_V(8); PG8_WAIT_L(0); PG8_BAR; PG8_MMA(0, 0, At, B0); PG8_MMA(0, 1, At, B1); PG8_BAR; PG8_SCHED;
	s_add_i32 s75, 0, 0x18000
	s_add_i32 s33, 0, 0x1c000
	v_add_u32_e32 v170, s75, v151
	v_add_u32_e32 v175, s33, v151
	s_add_u32 s76, s84, 0x40000
	s_addc_u32 s77, s85, 0
	s_mov_b32 m0, s87
	v_lshl_add_u64 v[232:233], s[76:77], 0, v[134:135]
	global_load_lds_dwordx4 v[232:233], off
	v_lshl_add_u64 v[232:233], s[76:77], 0, v[130:131]
	s_mov_b32 m0, s88
	s_nop 0
	global_load_lds_dwordx4 v[232:233], off
	ds_read_b128 v[146:149], v170
	ds_read_b128 v[162:165], v170 offset:1024
	ds_read_b128 v[166:169], v170 offset:2048
	ds_read_b128 v[170:173], v170 offset:3072
	ds_read_b128 v[176:179], v175
	ds_read_b128 v[180:183], v175 offset:1024
	ds_read_b128 v[184:187], v175 offset:2048
	ds_read_b128 v[188:191], v175 offset:3072
	ds_read_b128 v[192:195], v161 offset:32768
	ds_read_b128 v[196:199], v161 offset:33792
	ds_read_b128 v[200:203], v161 offset:34816
	ds_read_b128 v[204:207], v161 offset:35840
	ds_read_b128 v[208:211], v161 offset:36864
	ds_read_b128 v[212:215], v161 offset:37888
	ds_read_b128 v[216:219], v161 offset:38912
	ds_read_b128 v[220:223], v161 offset:39936
	s_waitcnt vmcnt(24)
	s_waitcnt lgkmcnt(0)
	s_barrier
	s_setprio 1
	s_waitcnt lgkmcnt(0)
	v_mfma_f32_16x16x32_bf16 v[124:127], v[146:149], v[192:195], v[124:127]
	v_mfma_f32_16x16x32_bf16 v[120:123], v[166:169], v[192:195], v[120:123]
	v_mfma_f32_16x16x32_bf16 v[116:119], v[146:149], v[200:203], v[116:119]
	v_mfma_f32_16x16x32_bf16 v[112:115], v[166:169], v[200:203], v[112:115]
	v_mfma_f32_16x16x32_bf16 v[108:111], v[146:149], v[208:211], v[108:111]
	v_mfma_f32_16x16x32_bf16 v[104:107], v[166:169], v[208:211], v[104:107]
	v_mfma_f32_16x16x32_bf16 v[100:103], v[146:149], v[216:219], v[100:103]
	v_mfma_f32_16x16x32_bf16 v[96:99], v[166:169], v[216:219], v[96:99]
	v_mfma_f32_16x16x32_bf16 v[124:127], v[162:165], v[196:199], v[124:127]
	v_mfma_f32_16x16x32_bf16 v[120:123], v[170:173], v[196:199], v[120:123]
	v_mfma_f32_16x16x32_bf16 v[116:119], v[162:165], v[204:207], v[116:119]
	v_mfma_f32_16x16x32_bf16 v[112:115], v[170:173], v[204:207], v[112:115]
	v_mfma_f32_16x16x32_bf16 v[108:111], v[162:165], v[212:215], v[108:111]
	v_mfma_f32_16x16x32_bf16 v[104:107], v[170:173], v[212:215], v[104:107]
	v_mfma_f32_16x16x32_bf16 v[100:103], v[162:165], v[220:223], v[100:103]
	v_mfma_f32_16x16x32_bf16 v[96:99], v[170:173], v[220:223], v[96:99]
	s_setprio 0
	s_setprio 1
	v_mfma_f32_16x16x32_bf16 v[68:71], v[176:179], v[192:195], v[68:71]
	v_mfma_f32_16x16x32_bf16 v[64:67], v[184:187], v[192:195], v[64:67]
	v_mfma_f32_16x16x32_bf16 v[56:59], v[176:179], v[200:203], v[56:59]
	v_mfma_f32_16x16x32_bf16 v[48:51], v[184:187], v[200:203], v[48:51]
	v_mfma_f32_16x16x32_bf16 v[44:47], v[176:179], v[208:211], v[44:47]
	v_mfma_f32_16x16x32_bf16 v[40:43], v[184:187], v[208:211], v[40:43]
	v_mfma_f32_16x16x32_bf16 v[36:39], v[176:179], v[216:219], v[36:39]
	v_mfma_f32_16x16x32_bf16 v[32:35], v[184:187], v[216:219], v[32:35]
	v_mfma_f32_16x16x32_bf16 v[68:71], v[180:183], v[196:199], v[68:71]
	v_mfma_f32_16x16x32_bf16 v[64:67], v[188:191], v[196:199], v[64:67]
	v_mfma_f32_16x16x32_bf16 v[56:59], v[180:183], v[204:207], v[56:59]
	v_mfma_f32_16x16x32_bf16 v[48:51], v[188:191], v[204:207], v[48:51]
	v_mfma_f32_16x16x32_bf16 v[44:47], v[180:183], v[212:215], v[44:47]
	v_mfma_f32_16x16x32_bf16 v[40:43], v[188:191], v[212:215], v[40:43]
	v_mfma_f32_16x16x32_bf16 v[36:39], v[180:183], v[220:223], v[36:39]
	v_mfma_f32_16x16x32_bf16 v[32:35], v[188:191], v[220:223], v[32:35]
	s_setprio 0
	s_barrier
; #define PG8_STAGE(bufoff, gbase, voff) do { _Pragma("unroll") for (int _i = 0; _i < 2; ++_i) \
;         __builtin_amdgcn_global_load_lds((const unsigned*)((const char*)(gbase) + (voff)[_i]), (PG8_LAS unsigned*)(lds + (bufoff) + ldsw + _i * 8192), 16, 0, 0); } while (0)
; #define PG8_LDA(dst, b, h) do { _Pragma("unroll") for (int m = 0; m < 4; ++m) _Pragma("unroll") for (int k = 0; k < 2; ++k) dst[m][k] = *(const PG8_LAS bf16x8*)(lds + PG8_SA(b, h) + aoff + m * 2048 + k * 1024); } while (0)
; #define PG8_MMA(ai, bj, At, Bt) do { __builtin_amdgcn_s_setprio(1); _Pragma("unroll") for (int m = 0; m < 4; ++m) _Pragma("unroll") for (int n = 0; n < 2; ++n) _Pragma("unroll") for (int k = 0; k < 2; ++k) \
;         acc[ai][bj][m][n] = __builtin_amdgcn_mfma_f32_16x16x32_bf16(Bt[n][k], At[m][k], acc[ai][bj][m][n], 0, 0, 0); __builtin_amdgcn_s_setprio(0); } while (0)
; #define PG8_WAIT_V(n) asm volatile("s_waitcnt vmcnt(" #n ")" ::: "memory")
; #define PG8_WAIT_L(n) asm volatile("s_waitcnt lgkmcnt(" #n ")" ::: "memory")
; #define PG8_BAR __builtin_amdgcn_s_barrier()
; #define PG8_SCHED __builtin_amdgcn_sched_barrier(0)
; template <class Epi, class Sched, bool ALIGN_EPI = false, bool SP2 = false>
; __device__ __forceinline__ void gemm_phase(PG8_LAS unsigned char* lds, const Gemm g, const Sched& S, const Epi& E) {
;     ...
;             PG8_LDA(At, 1, 1); PG8_STAGE(PG8_SB(1, 0), b3, voffB); PG8_STAGE(PG8_SB(1, 1), b3 + hstepB, voffB); PG8_STAGE(PG8_SA(1, 0), a3, voffA);
;             PG8_WAIT_V(8); PG8_WAIT_L(0); PG8_BAR; PG8_MMA(1, 0, At, B0); PG8_MMA(1, 1, At, B1); PG8_BAR; PG8_SCHED;
	s_add_i32 s75, s75, s27
	v_lshl_add_u64 v[224:225], v[224:225], 0, s[8:9]
	s_mov_b32 m0, s75
	global_load_lds_dwordx4 v[224:225], off
	s_add_i32 m0, s75, 0x2000
	s_add_u32 s66, s66, 0x40080
	v_lshl_add_u64 v[224:225], v[226:227], 0, s[8:9]
	s_addc_u32 s67, s67, 0
	s_add_i32 s33, s33, s27
	global_load_lds_dwordx4 v[224:225], off
	v_lshl_add_u64 v[224:225], s[66:67], 0, v[132:133]
	s_mov_b32 m0, s33
	s_nop 0
	global_load_lds_dwordx4 v[224:225], off
	v_lshl_add_u64 v[224:225], s[66:67], 0, v[128:129]
	s_add_i32 m0, s33, 0x2000
	s_nop 0
	global_load_lds_dwordx4 v[224:225], off
	v_lshl_add_u64 v[224:225], v[228:229], 0, s[8:9]
	s_mov_b32 m0, s91
	s_nop 0
	global_load_lds_dwordx4 v[224:225], off
	v_lshl_add_u64 v[224:225], v[230:231], 0, s[8:9]
	s_mov_b32 m0, s92
	s_nop 0
	global_load_lds_dwordx4 v[224:225], off
	ds_read_b128 v[192:195], v161 offset:49152
	ds_read_b128 v[196:199], v161 offset:50176
	ds_read_b128 v[200:203], v161 offset:51200
	ds_read_b128 v[204:207], v161 offset:52224
	ds_read_b128 v[208:211], v161 offset:53248
	ds_read_b128 v[212:215], v161 offset:54272
	ds_read_b128 v[216:219], v161 offset:55296
	ds_read_b128 v[220:223], v161 offset:56320
	s_waitcnt vmcnt(8)
	s_waitcnt lgkmcnt(0)
	s_barrier
	s_setprio 1
	s_waitcnt lgkmcnt(0)
	v_mfma_f32_16x16x32_bf16 v[92:95], v[146:149], v[192:195], v[92:95]
	v_mfma_f32_16x16x32_bf16 v[88:91], v[166:169], v[192:195], v[88:91]
	v_mfma_f32_16x16x32_bf16 v[84:87], v[146:149], v[200:203], v[84:87]
	v_mfma_f32_16x16x32_bf16 v[80:83], v[166:169], v[200:203], v[80:83]
	v_mfma_f32_16x16x32_bf16 v[76:79], v[146:149], v[208:211], v[76:79]
	v_mfma_f32_16x16x32_bf16 v[72:75], v[166:169], v[208:211], v[72:75]
	v_mfma_f32_16x16x32_bf16 v[60:63], v[146:149], v[216:219], v[60:63]
	v_mfma_f32_16x16x32_bf16 v[52:55], v[166:169], v[216:219], v[52:55]
	v_mfma_f32_16x16x32_bf16 v[92:95], v[162:165], v[196:199], v[92:95]
	v_mfma_f32_16x16x32_bf16 v[88:91], v[170:173], v[196:199], v[88:91]
	v_mfma_f32_16x16x32_bf16 v[84:87], v[162:165], v[204:207], v[84:87]
	v_mfma_f32_16x16x32_bf16 v[80:83], v[170:173], v[204:207], v[80:83]
	v_mfma_f32_16x16x32_bf16 v[76:79], v[162:165], v[212:215], v[76:79]
	v_mfma_f32_16x16x32_bf16 v[72:75], v[170:173], v[212:215], v[72:75]
	v_mfma_f32_16x16x32_bf16 v[60:63], v[162:165], v[220:223], v[60:63]
	v_mfma_f32_16x16x32_bf16 v[52:55], v[170:173], v[220:223], v[52:55]
	s_setprio 0
	s_setprio 1
	v_mfma_f32_16x16x32_bf16 v[28:31], v[176:179], v[192:195], v[28:31]
	v_mfma_f32_16x16x32_bf16 v[24:27], v[184:187], v[192:195], v[24:27]
	v_mfma_f32_16x16x32_bf16 v[20:23], v[176:179], v[200:203], v[20:23]
	v_mfma_f32_16x16x32_bf16 v[16:19], v[184:187], v[200:203], v[16:19]
	v_mfma_f32_16x16x32_bf16 v[12:15], v[176:179], v[208:211], v[12:15]
	v_mfma_f32_16x16x32_bf16 v[8:11], v[184:187], v[208:211], v[8:11]
	v_mfma_f32_16x16x32_bf16 v[4:7], v[176:179], v[216:219], v[4:7]
	v_mfma_f32_16x16x32_bf16 v[0:3], v[184:187], v[216:219], v[0:3]
	v_mfma_f32_16x16x32_bf16 v[28:31], v[180:183], v[196:199], v[28:31]
	v_mfma_f32_16x16x32_bf16 v[24:27], v[188:191], v[196:199], v[24:27]
	v_mfma_f32_16x16x32_bf16 v[20:23], v[180:183], v[204:207], v[20:23]
	v_mfma_f32_16x16x32_bf16 v[16:19], v[188:191], v[204:207], v[16:19]
	v_mfma_f32_16x16x32_bf16 v[12:15], v[180:183], v[212:215], v[12:15]
	v_mfma_f32_16x16x32_bf16 v[8:11], v[188:191], v[212:215], v[8:11]
	v_mfma_f32_16x16x32_bf16 v[4:7], v[180:183], v[220:223], v[4:7]
	v_mfma_f32_16x16x32_bf16 v[0:3], v[188:191], v[220:223], v[0:3]
	s_setprio 0
	s_barrier
	s_add_i32 s74, s74, 2
	s_add_u32 s60, s60, 0x100
	s_addc_u32 s61, s61, 0
	s_add_u32 s80, s80, 0x100
	s_addc_u32 s81, s81, 0
	s_cmp_gt_u32 s74, 13
	s_branch .LBB0_197

; #define PG8_STAGE(bufoff, gbase, voff) do { _Pragma("unroll") for (int _i = 0; _i < 2; ++_i) \
;         __builtin_amdgcn_global_load_lds((const unsigned*)((const char*)(gbase) + (voff)[_i]), (PG8_LAS unsigned*)(lds + (bufoff) + ldsw + _i * 8192), 16, 0, 0); } while (0)
; #define PG8_LDA(dst, b, h) do { _Pragma("unroll") for (int m = 0; m < 4; ++m) _Pragma("unroll") for (int k = 0; k < 2; ++k) dst[m][k] = *(const PG8_LAS bf16x8*)(lds + PG8_SA(b, h) + aoff + m * 2048 + k * 1024); } while (0)
; #define PG8_LDB(dst, b, h) do { _Pragma("unroll") for (int n = 0; n < 2; ++n) _Pragma("unroll") for (int k = 0; k < 2; ++k) dst[n][k] = *(const PG8_LAS bf16x8*)(lds + PG8_SB(b, h) + boff + n * 2048 + k * 1024); } while (0)
; #define PG8_MMA(ai, bj, At, Bt) do { __builtin_amdgcn_s_setprio(1); _Pragma("unroll") for (int m = 0; m < 4; ++m) _Pragma("unroll") for (int n = 0; n < 2; ++n) _Pragma("unroll") for (int k = 0; k < 2; ++k) \
;         acc[ai][bj][m][n] = __builtin_amdgcn_mfma_f32_16x16x32_bf16(Bt[n][k], At[m][k], acc[ai][bj][m][n], 0, 0, 0); __builtin_amdgcn_s_setprio(0); } while (0)
; #define PG8_WAIT_V(n) asm volatile("s_waitcnt vmcnt(" #n ")" ::: "memory")
; #define PG8_WAIT_L(n) asm volatile("s_waitcnt lgkmcnt(" #n ")" ::: "memory")
; #define PG8_BAR __builtin_amdgcn_s_barrier()
; #define PG8_SCHED __builtin_amdgcn_sched_barrier(0)
; template <class Epi, class Sched, bool ALIGN_EPI = false, bool SP2 = false>
; __device__ __forceinline__ void gemm_phase(PG8_LAS unsigned char* lds, const Gemm g, const Sched& S, const Epi& E) {
;     ...
;             PG8_LDB(B0, 0, 0); PG8_LDB(B1, 0, 1); PG8_SCHED; PG8_LDA(At, 0, 0); PG8_STAGE(PG8_SA(1, 1), a1 + hstepA, voffA);
;             PG8_WAIT_V(8); PG8_WAIT_L(0); PG8_BAR; PG8_MMA(0, 0, At, B0); PG8_MMA(0, 1, At, B1); PG8_BAR; PG8_SCHED;
;             PG8_LDA(At, 0, 1); PG8_STAGE(PG8_SB(0, 0), b2, voffB); PG8_STAGE(PG8_SB(0, 1), b2 + hstepB, voffB); PG8_STAGE(PG8_SA(0, 0), a2, voffA);
;             PG8_WAIT_V(8); PG8_WAIT_L(0); PG8_BAR; PG8_MMA(1, 0, At, B0); PG8_MMA(1, 1, At, B1); PG8_BAR; PG8_SCHED;
.LBB0_605:
	s_add_u32 s33, s38, 0xfffc0080
	s_addc_u32 s40, s39, -1
	s_cmp_eq_u32 s56, 12
	s_cselect_b32 s43, s13, s40
	s_cselect_b32 s42, s52, s33
	s_cselect_b32 s41, s11, s55
	s_cselect_b32 s40, s53, s54
	v_lshl_add_u64 v[216:217], s[38:39], 0, v[136:137]
	s_add_i32 m0, s29, 0xc000
	global_load_lds_dwordx4 v[216:217], off
	v_lshl_add_u64 v[216:217], s[38:39], 0, v[138:139]
	s_add_i32 m0, s29, 0xe000
	s_nop 0
	global_load_lds_dwordx4 v[216:217], off
	ds_read_b128 v[144:147], v151
	ds_read_b128 v[154:157], v151 offset:1024
	ds_read_b128 v[158:161], v151 offset:2048
	ds_read_b128 v[162:165], v151 offset:3072
	ds_read_b128 v[166:169], v152
	ds_read_b128 v[170:173], v152 offset:1024
	ds_read_b128 v[176:179], v152 offset:2048
	ds_read_b128 v[180:183], v152 offset:3072
	ds_read_b128 v[184:187], v153
	ds_read_b128 v[188:191], v153 offset:1024
	ds_read_b128 v[192:195], v153 offset:2048
	ds_read_b128 v[196:199], v153 offset:3072
	ds_read_b128 v[200:203], v153 offset:4096
	ds_read_b128 v[204:207], v153 offset:5120
	ds_read_b128 v[208:211], v153 offset:6144
	ds_read_b128 v[212:215], v153 offset:7168
	s_waitcnt vmcnt(8)
	s_waitcnt lgkmcnt(0)
	s_barrier
	s_setprio 1
	s_waitcnt lgkmcnt(0)
	v_mfma_f32_16x16x32_bf16 v[124:127], v[144:147], v[184:187], v[124:127]
	v_mfma_f32_16x16x32_bf16 v[120:123], v[158:161], v[184:187], v[120:123]
	v_mfma_f32_16x16x32_bf16 v[108:111], v[144:147], v[192:195], v[108:111]
	v_mfma_f32_16x16x32_bf16 v[104:107], v[158:161], v[192:195], v[104:107]
	v_mfma_f32_16x16x32_bf16 v[92:95], v[144:147], v[200:203], v[92:95]
	v_mfma_f32_16x16x32_bf16 v[88:91], v[158:161], v[200:203], v[88:91]
	v_mfma_f32_16x16x32_bf16 v[76:79], v[144:147], v[208:211], v[76:79]
	v_mfma_f32_16x16x32_bf16 v[72:75], v[158:161], v[208:211], v[72:75]
	v_mfma_f32_16x16x32_bf16 v[124:127], v[154:157], v[188:191], v[124:127]
	v_mfma_f32_16x16x32_bf16 v[120:123], v[162:165], v[188:191], v[120:123]
	v_mfma_f32_16x16x32_bf16 v[108:111], v[154:157], v[196:199], v[108:111]
	v_mfma_f32_16x16x32_bf16 v[104:107], v[162:165], v[196:199], v[104:107]
	v_mfma_f32_16x16x32_bf16 v[92:95], v[154:157], v[204:207], v[92:95]
	v_mfma_f32_16x16x32_bf16 v[88:91], v[162:165], v[204:207], v[88:91]
	v_mfma_f32_16x16x32_bf16 v[76:79], v[154:157], v[212:215], v[76:79]
	v_mfma_f32_16x16x32_bf16 v[72:75], v[162:165], v[212:215], v[72:75]
	s_setprio 0
	s_setprio 1
	v_mfma_f32_16x16x32_bf16 v[116:119], v[166:169], v[184:187], v[116:119]
	v_mfma_f32_16x16x32_bf16 v[112:115], v[176:179], v[184:187], v[112:115]
	v_mfma_f32_16x16x32_bf16 v[100:103], v[166:169], v[192:195], v[100:103]
	v_mfma_f32_16x16x32_bf16 v[96:99], v[176:179], v[192:195], v[96:99]
	v_mfma_f32_16x16x32_bf16 v[84:87], v[166:169], v[200:203], v[84:87]
	v_mfma_f32_16x16x32_bf16 v[80:83], v[176:179], v[200:203], v[80:83]
	v_mfma_f32_16x16x32_bf16 v[68:71], v[166:169], v[208:211], v[68:71]
	v_mfma_f32_16x16x32_bf16 v[64:67], v[176:179], v[208:211], v[64:67]
	v_mfma_f32_16x16x32_bf16 v[116:119], v[170:173], v[188:191], v[116:119]
	v_mfma_f32_16x16x32_bf16 v[112:115], v[180:183], v[188:191], v[112:115]
	v_mfma_f32_16x16x32_bf16 v[100:103], v[170:173], v[196:199], v[100:103]
	v_mfma_f32_16x16x32_bf16 v[96:99], v[180:183], v[196:199], v[96:99]
	v_mfma_f32_16x16x32_bf16 v[84:87], v[170:173], v[204:207], v[84:87]
	v_mfma_f32_16x16x32_bf16 v[80:83], v[180:183], v[204:207], v[80:83]
	v_mfma_f32_16x16x32_bf16 v[68:71], v[170:173], v[212:215], v[68:71]
	v_mfma_f32_16x16x32_bf16 v[64:67], v[180:183], v[212:215], v[64:67]
	s_setprio 0
	s_barrier
	s_add_i32 s33, s48, s22
	v_lshl_add_u64 v[216:217], s[40:41], 0, v[132:133]
	s_mov_b32 m0, s33
	global_load_lds_dwordx4 v[216:217], off
	s_add_i32 m0, s33, 0x2000
	s_add_u32 s58, s40, 0x40000
	v_lshl_add_u64 v[218:219], s[40:41], 0, v[128:129]
	s_addc_u32 s59, s41, 0
	s_add_i32 s33, s49, s22
	global_load_lds_dwordx4 v[218:219], off
	v_lshl_add_u64 v[220:221], s[58:59], 0, v[132:133]
	s_mov_b32 m0, s33
	v_lshl_add_u64 v[222:223], s[42:43], 0, v[130:131]
	global_load_lds_dwordx4 v[220:221], off
	v_lshl_add_u64 v[220:221], s[58:59], 0, v[128:129]
	s_add_i32 m0, s33, 0x2000
	s_nop 0
	global_load_lds_dwordx4 v[220:221], off
	v_lshl_add_u64 v[220:221], s[42:43], 0, v[134:135]
	s_mov_b32 m0, s29
	s_nop 0
	global_load_lds_dwordx4 v[220:221], off
	s_mov_b32 m0, s30
	s_nop 0
	global_load_lds_dwordx4 v[222:223], off
	ds_read_b128 v[184:187], v153 offset:16384
	ds_read_b128 v[188:191], v153 offset:17408
	ds_read_b128 v[192:195], v153 offset:18432
	ds_read_b128 v[196:199], v153 offset:19456
	ds_read_b128 v[200:203], v153 offset:20480
	ds_read_b128 v[204:207], v153 offset:21504
	ds_read_b128 v[208:211], v153 offset:22528
	ds_read_b128 v[212:215], v153 offset:23552
	s_waitcnt vmcnt(8)
	s_waitcnt lgkmcnt(0)
	s_barrier
; #define PG8_STAGE(bufoff, gbase, voff) do { _Pragma("unroll") for (int _i = 0; _i < 2; ++_i) \
;         __builtin_amdgcn_global_load_lds((const unsigned*)((const char*)(gbase) + (voff)[_i]), (PG8_LAS unsigned*)(lds + (bufoff) + ldsw + _i * 8192), 16, 0, 0); } while (0)
; #define PG8_LDA(dst, b, h) do { _Pragma("unroll") for (int m = 0; m < 4; ++m) _Pragma("unroll") for (int k = 0; k < 2; ++k) dst[m][k] = *(const PG8_LAS bf16x8*)(lds + PG8_SA(b, h) + aoff + m * 2048 + k * 1024); } while (0)
; #define PG8_LDB(dst, b, h) do { _Pragma("unroll") for (int n = 0; n < 2; ++n) _Pragma("unroll") for (int k = 0; k < 2; ++k) dst[n][k] = *(const PG8_LAS bf16x8*)(lds + PG8_SB(b, h) + boff + n * 2048 + k * 1024); } while (0)
; #define PG8_MMA(ai, bj, At, Bt) do { __builtin_amdgcn_s_setprio(1); _Pragma("unroll") for (int m = 0; m < 4; ++m) _Pragma("unroll") for (int n = 0; n < 2; ++n) _Pragma("unroll") for (int k = 0; k < 2; ++k) \
;         acc[ai][bj][m][n] = __builtin_amdgcn_mfma_f32_16x16x32_bf16(Bt[n][k], At[m][k], acc[ai][bj][m][n], 0, 0, 0); __builtin_amdgcn_s_setprio(0); } while (0)
; #define PG8_WAIT_V(n) asm volatile("s_waitcnt vmcnt(" #n ")" ::: "memory")
; #define PG8_WAIT_L(n) asm volatile("s_waitcnt lgkmcnt(" #n ")" ::: "memory")
; #define PG8_BAR __builtin_amdgcn_s_barrier()
; #define PG8_SCHED __builtin_amdgcn_sched_barrier(0)
; template <class Epi, class Sched, bool ALIGN_EPI = false, bool SP2 = false>
; __device__ __forceinline__ void gemm_phase(PG8_LAS unsigned char* lds, const Gemm g, const Sched& S, const Epi& E) {
;     ...
;             PG8_WAIT_V(8); PG8_WAIT_L(0); PG8_BAR; PG8_MMA(1, 0, At, B0); PG8_MMA(1, 1, At, B1); PG8_BAR; PG8_SCHED;
;             PG8_LDB(B0, 1, 0); PG8_LDB(B1, 1, 1); PG8_SCHED; PG8_LDA(At, 1, 0); PG8_STAGE(PG8_SA(0, 1), a2 + hstepA, voffA);
;             PG8_WAIT_V(8); PG8_WAIT_L(0); PG8_BAR; PG8_MMA(0, 0, At, B0); PG8_MMA(0, 1, At, B1); PG8_BAR; PG8_SCHED;
	s_setprio 1
	s_waitcnt lgkmcnt(0)
	v_mfma_f32_16x16x32_bf16 v[60:63], v[144:147], v[184:187], v[60:63]
	v_mfma_f32_16x16x32_bf16 v[56:59], v[158:161], v[184:187], v[56:59]
	v_mfma_f32_16x16x32_bf16 v[44:47], v[144:147], v[192:195], v[44:47]
	v_mfma_f32_16x16x32_bf16 v[40:43], v[158:161], v[192:195], v[40:43]
	v_mfma_f32_16x16x32_bf16 v[28:31], v[144:147], v[200:203], v[28:31]
	v_mfma_f32_16x16x32_bf16 v[24:27], v[158:161], v[200:203], v[24:27]
	v_mfma_f32_16x16x32_bf16 v[12:15], v[144:147], v[208:211], v[12:15]
	v_mfma_f32_16x16x32_bf16 v[8:11], v[158:161], v[208:211], v[8:11]
	v_mfma_f32_16x16x32_bf16 v[60:63], v[154:157], v[188:191], v[60:63]
	v_mfma_f32_16x16x32_bf16 v[56:59], v[162:165], v[188:191], v[56:59]
	v_mfma_f32_16x16x32_bf16 v[44:47], v[154:157], v[196:199], v[44:47]
	v_mfma_f32_16x16x32_bf16 v[40:43], v[162:165], v[196:199], v[40:43]
	v_mfma_f32_16x16x32_bf16 v[28:31], v[154:157], v[204:207], v[28:31]
	v_mfma_f32_16x16x32_bf16 v[24:27], v[162:165], v[204:207], v[24:27]
	v_mfma_f32_16x16x32_bf16 v[12:15], v[154:157], v[212:215], v[12:15]
	v_mfma_f32_16x16x32_bf16 v[8:11], v[162:165], v[212:215], v[8:11]
	s_setprio 0
	s_setprio 1
	v_mfma_f32_16x16x32_bf16 v[52:55], v[166:169], v[184:187], v[52:55]
	v_mfma_f32_16x16x32_bf16 v[48:51], v[176:179], v[184:187], v[48:51]
	v_mfma_f32_16x16x32_bf16 v[36:39], v[166:169], v[192:195], v[36:39]
	v_mfma_f32_16x16x32_bf16 v[32:35], v[176:179], v[192:195], v[32:35]
	v_mfma_f32_16x16x32_bf16 v[20:23], v[166:169], v[200:203], v[20:23]
	v_mfma_f32_16x16x32_bf16 v[16:19], v[176:179], v[200:203], v[16:19]
	v_mfma_f32_16x16x32_bf16 v[4:7], v[166:169], v[208:211], v[4:7]
	v_mfma_f32_16x16x32_bf16 v[0:3], v[176:179], v[208:211], v[0:3]
	v_mfma_f32_16x16x32_bf16 v[52:55], v[170:173], v[188:191], v[52:55]
	v_mfma_f32_16x16x32_bf16 v[48:51], v[180:183], v[188:191], v[48:51]
	v_mfma_f32_16x16x32_bf16 v[36:39], v[170:173], v[196:199], v[36:39]
	v_mfma_f32_16x16x32_bf16 v[32:35], v[180:183], v[196:199], v[32:35]
	v_mfma_f32_16x16x32_bf16 v[20:23], v[170:173], v[204:207], v[20:23]
	v_mfma_f32_16x16x32_bf16 v[16:19], v[180:183], v[204:207], v[16:19]
	v_mfma_f32_16x16x32_bf16 v[4:7], v[170:173], v[212:215], v[4:7]
	v_mfma_f32_16x16x32_bf16 v[0:3], v[180:183], v[212:215], v[0:3]
	s_setprio 0
	s_barrier
	s_add_i32 s33, 0, 0x18000
	s_add_i32 s57, 0, 0x1c000
	v_add_u32_e32 v162, s33, v149
	v_add_u32_e32 v175, s57, v149
	s_add_u32 s42, s42, 0x40000
	s_addc_u32 s43, s43, 0
	s_mov_b32 m0, s31
	v_lshl_add_u64 v[224:225], s[42:43], 0, v[134:135]
	global_load_lds_dwordx4 v[224:225], off
	v_lshl_add_u64 v[224:225], s[42:43], 0, v[130:131]
	s_mov_b32 m0, s35
	s_nop 0
	global_load_lds_dwordx4 v[224:225], off
	ds_read_b128 v[144:147], v162
	ds_read_b128 v[154:157], v162 offset:1024
	ds_read_b128 v[158:161], v162 offset:2048
	ds_read_b128 v[162:165], v162 offset:3072
	ds_read_b128 v[166:169], v175
	ds_read_b128 v[170:173], v175 offset:1024
	ds_read_b128 v[176:179], v175 offset:2048
	ds_read_b128 v[180:183], v175 offset:3072
	ds_read_b128 v[184:187], v153 offset:32768
	ds_read_b128 v[188:191], v153 offset:33792
	ds_read_b128 v[192:195], v153 offset:34816
	ds_read_b128 v[196:199], v153 offset:35840
	ds_read_b128 v[200:203], v153 offset:36864
	ds_read_b128 v[204:207], v153 offset:37888
	ds_read_b128 v[208:211], v153 offset:38912
	ds_read_b128 v[212:215], v153 offset:39936
	s_waitcnt vmcnt(8)
	s_waitcnt lgkmcnt(0)
	s_barrier
	s_setprio 1
	s_waitcnt lgkmcnt(0)
	v_mfma_f32_16x16x32_bf16 v[124:127], v[144:147], v[184:187], v[124:127]
	v_mfma_f32_16x16x32_bf16 v[120:123], v[158:161], v[184:187], v[120:123]
	v_mfma_f32_16x16x32_bf16 v[108:111], v[144:147], v[192:195], v[108:111]
	v_mfma_f32_16x16x32_bf16 v[104:107], v[158:161], v[192:195], v[104:107]
	v_mfma_f32_16x16x32_bf16 v[92:95], v[144:147], v[200:203], v[92:95]
	v_mfma_f32_16x16x32_bf16 v[88:91], v[158:161], v[200:203], v[88:91]
	v_mfma_f32_16x16x32_bf16 v[76:79], v[144:147], v[208:211], v[76:79]
	v_mfma_f32_16x16x32_bf16 v[72:75], v[158:161], v[208:211], v[72:75]
	v_mfma_f32_16x16x32_bf16 v[124:127], v[154:157], v[188:191], v[124:127]
	v_mfma_f32_16x16x32_bf16 v[120:123], v[162:165], v[188:191], v[120:123]
	v_mfma_f32_16x16x32_bf16 v[108:111], v[154:157], v[196:199], v[108:111]
	v_mfma_f32_16x16x32_bf16 v[104:107], v[162:165], v[196:199], v[104:107]
	v_mfma_f32_16x16x32_bf16 v[92:95], v[154:157], v[204:207], v[92:95]
	v_mfma_f32_16x16x32_bf16 v[88:91], v[162:165], v[204:207], v[88:91]
	v_mfma_f32_16x16x32_bf16 v[76:79], v[154:157], v[212:215], v[76:79]
	v_mfma_f32_16x16x32_bf16 v[72:75], v[162:165], v[212:215], v[72:75]
	s_setprio 0
	s_setprio 1
	v_mfma_f32_16x16x32_bf16 v[116:119], v[166:169], v[184:187], v[116:119]
	v_mfma_f32_16x16x32_bf16 v[112:115], v[176:179], v[184:187], v[112:115]
	v_mfma_f32_16x16x32_bf16 v[100:103], v[166:169], v[192:195], v[100:103]
	v_mfma_f32_16x16x32_bf16 v[96:99], v[176:179], v[192:195], v[96:99]
	v_mfma_f32_16x16x32_bf16 v[84:87], v[166:169], v[200:203], v[84:87]
	v_mfma_f32_16x16x32_bf16 v[80:83], v[176:179], v[200:203], v[80:83]
	v_mfma_f32_16x16x32_bf16 v[68:71], v[166:169], v[208:211], v[68:71]
	v_mfma_f32_16x16x32_bf16 v[64:67], v[176:179], v[208:211], v[64:67]
	v_mfma_f32_16x16x32_bf16 v[116:119], v[170:173], v[188:191], v[116:119]
	v_mfma_f32_16x16x32_bf16 v[112:115], v[180:183], v[188:191], v[112:115]
	v_mfma_f32_16x16x32_bf16 v[100:103], v[170:173], v[196:199], v[100:103]
	v_mfma_f32_16x16x32_bf16 v[96:99], v[180:183], v[196:199], v[96:99]
	v_mfma_f32_16x16x32_bf16 v[84:87], v[170:173], v[204:207], v[84:87]
	v_mfma_f32_16x16x32_bf16 v[80:83], v[180:183], v[204:207], v[80:83]
	v_mfma_f32_16x16x32_bf16 v[68:71], v[170:173], v[212:215], v[68:71]
	v_mfma_f32_16x16x32_bf16 v[64:67], v[180:183], v[212:215], v[64:67]
	s_setprio 0
	s_barrier
; #define PG8_STAGE(bufoff, gbase, voff) do { _Pragma("unroll") for (int _i = 0; _i < 2; ++_i) \
;         __builtin_amdgcn_global_load_lds((const unsigned*)((const char*)(gbase) + (voff)[_i]), (PG8_LAS unsigned*)(lds + (bufoff) + ldsw + _i * 8192), 16, 0, 0); } while (0)
; #define PG8_LDA(dst, b, h) do { _Pragma("unroll") for (int m = 0; m < 4; ++m) _Pragma("unroll") for (int k = 0; k < 2; ++k) dst[m][k] = *(const PG8_LAS bf16x8*)(lds + PG8_SA(b, h) + aoff + m * 2048 + k * 1024); } while (0)
; #define PG8_MMA(ai, bj, At, Bt) do { __builtin_amdgcn_s_setprio(1); _Pragma("unroll") for (int m = 0; m < 4; ++m) _Pragma("unroll") for (int n = 0; n < 2; ++n) _Pragma("unroll") for (int k = 0; k < 2; ++k) \
;         acc[ai][bj][m][n] = __builtin_amdgcn_mfma_f32_16x16x32_bf16(Bt[n][k], At[m][k], acc[ai][bj][m][n], 0, 0, 0); __builtin_amdgcn_s_setprio(0); } while (0)
; #define PG8_WAIT_V(n) asm volatile("s_waitcnt vmcnt(" #n ")" ::: "memory")
; #define PG8_WAIT_L(n) asm volatile("s_waitcnt lgkmcnt(" #n ")" ::: "memory")
; #define PG8_BAR __builtin_amdgcn_s_barrier()
; #define PG8_SCHED __builtin_amdgcn_sched_barrier(0)
; template <class Epi, class Sched, bool ALIGN_EPI = false, bool SP2 = false>
; __device__ __forceinline__ void gemm_phase(PG8_LAS unsigned char* lds, const Gemm g, const Sched& S, const Epi& E) {
;     ...
;             PG8_LDA(At, 1, 1); PG8_STAGE(PG8_SB(1, 0), b3, voffB); PG8_STAGE(PG8_SB(1, 1), b3 + hstepB, voffB); PG8_STAGE(PG8_SA(1, 0), a3, voffA);
;             PG8_WAIT_V(8); PG8_WAIT_L(0); PG8_BAR; PG8_MMA(1, 0, At, B0); PG8_MMA(1, 1, At, B1); PG8_BAR; PG8_SCHED;
;     ...
;         if constexpr (ALIGN_EPI) { if (wr == 0) PG8_BAR; }
	s_add_i32 s33, s33, s22
	v_lshl_add_u64 v[216:217], v[216:217], 0, s[6:7]
	s_mov_b32 m0, s33
	global_load_lds_dwordx4 v[216:217], off
	s_add_i32 m0, s33, 0x2000
	s_add_u32 s40, s40, 0x40080
	v_lshl_add_u64 v[216:217], v[218:219], 0, s[6:7]
	s_addc_u32 s41, s41, 0
	s_add_i32 s33, s57, s22
	global_load_lds_dwordx4 v[216:217], off
	v_lshl_add_u64 v[216:217], s[40:41], 0, v[132:133]
	s_mov_b32 m0, s33
	s_nop 0
	global_load_lds_dwordx4 v[216:217], off
	v_lshl_add_u64 v[216:217], s[40:41], 0, v[128:129]
	s_add_i32 m0, s33, 0x2000
	s_nop 0
	global_load_lds_dwordx4 v[216:217], off
	v_lshl_add_u64 v[216:217], v[220:221], 0, s[6:7]
	s_mov_b32 m0, s44
	s_nop 0
	global_load_lds_dwordx4 v[216:217], off
	v_lshl_add_u64 v[216:217], v[222:223], 0, s[6:7]
	s_mov_b32 m0, s45
	s_nop 0
	global_load_lds_dwordx4 v[216:217], off
	ds_read_b128 v[184:187], v153 offset:49152
	ds_read_b128 v[188:191], v153 offset:50176
	ds_read_b128 v[192:195], v153 offset:51200
	ds_read_b128 v[196:199], v153 offset:52224
	ds_read_b128 v[200:203], v153 offset:53248
	ds_read_b128 v[204:207], v153 offset:54272
	ds_read_b128 v[208:211], v153 offset:55296
	ds_read_b128 v[212:215], v153 offset:56320
	s_waitcnt vmcnt(8)
	s_waitcnt lgkmcnt(0)
	s_barrier
	s_setprio 1
	s_waitcnt lgkmcnt(0)
	v_mfma_f32_16x16x32_bf16 v[60:63], v[144:147], v[184:187], v[60:63]
	v_mfma_f32_16x16x32_bf16 v[56:59], v[158:161], v[184:187], v[56:59]
	v_mfma_f32_16x16x32_bf16 v[44:47], v[144:147], v[192:195], v[44:47]
	v_mfma_f32_16x16x32_bf16 v[40:43], v[158:161], v[192:195], v[40:43]
	v_mfma_f32_16x16x32_bf16 v[28:31], v[144:147], v[200:203], v[28:31]
	v_mfma_f32_16x16x32_bf16 v[24:27], v[158:161], v[200:203], v[24:27]
	v_mfma_f32_16x16x32_bf16 v[12:15], v[144:147], v[208:211], v[12:15]
	v_mfma_f32_16x16x32_bf16 v[8:11], v[158:161], v[208:211], v[8:11]
	v_mfma_f32_16x16x32_bf16 v[60:63], v[154:157], v[188:191], v[60:63]
	v_mfma_f32_16x16x32_bf16 v[56:59], v[162:165], v[188:191], v[56:59]
	v_mfma_f32_16x16x32_bf16 v[44:47], v[154:157], v[196:199], v[44:47]
	v_mfma_f32_16x16x32_bf16 v[40:43], v[162:165], v[196:199], v[40:43]
	v_mfma_f32_16x16x32_bf16 v[28:31], v[154:157], v[204:207], v[28:31]
	v_mfma_f32_16x16x32_bf16 v[24:27], v[162:165], v[204:207], v[24:27]
	v_mfma_f32_16x16x32_bf16 v[12:15], v[154:157], v[212:215], v[12:15]
	v_mfma_f32_16x16x32_bf16 v[8:11], v[162:165], v[212:215], v[8:11]
	s_setprio 0
	s_setprio 1
	v_mfma_f32_16x16x32_bf16 v[52:55], v[166:169], v[184:187], v[52:55]
	v_mfma_f32_16x16x32_bf16 v[48:51], v[176:179], v[184:187], v[48:51]
	v_mfma_f32_16x16x32_bf16 v[36:39], v[166:169], v[192:195], v[36:39]
	v_mfma_f32_16x16x32_bf16 v[32:35], v[176:179], v[192:195], v[32:35]
	v_mfma_f32_16x16x32_bf16 v[20:23], v[166:169], v[200:203], v[20:23]
	v_mfma_f32_16x16x32_bf16 v[16:19], v[176:179], v[200:203], v[16:19]
	v_mfma_f32_16x16x32_bf16 v[4:7], v[166:169], v[208:211], v[4:7]
	v_mfma_f32_16x16x32_bf16 v[0:3], v[176:179], v[208:211], v[0:3]
	v_mfma_f32_16x16x32_bf16 v[52:55], v[170:173], v[188:191], v[52:55]
	v_mfma_f32_16x16x32_bf16 v[48:51], v[180:183], v[188:191], v[48:51]
	v_mfma_f32_16x16x32_bf16 v[36:39], v[170:173], v[196:199], v[36:39]
	v_mfma_f32_16x16x32_bf16 v[32:35], v[180:183], v[196:199], v[32:35]
	v_mfma_f32_16x16x32_bf16 v[20:23], v[170:173], v[204:207], v[20:23]
	v_mfma_f32_16x16x32_bf16 v[16:19], v[180:183], v[204:207], v[16:19]
	v_mfma_f32_16x16x32_bf16 v[4:7], v[170:173], v[212:215], v[4:7]
	v_mfma_f32_16x16x32_bf16 v[0:3], v[180:183], v[212:215], v[0:3]
	s_setprio 0
	s_barrier
	s_add_i32 s56, s56, 2
	s_add_u32 s38, s38, 0x100
	s_addc_u32 s39, s39, 0
	s_add_u32 s54, s54, 0x100
	s_addc_u32 s55, s55, 0
	s_cmp_gt_u32 s56, 13
	s_cbranch_scc0 .LBB0_605
	s_and_b64 vcc, exec, s[8:9]
	s_cbranch_vccz .LBB0_608
	s_barrier

; #define PG8_STAGE(bufoff, gbase, voff) do { _Pragma("unroll") for (int _i = 0; _i < 2; ++_i) \
;         __builtin_amdgcn_global_load_lds((const unsigned*)((const char*)(gbase) + (voff)[_i]), (PG8_LAS unsigned*)(lds + (bufoff) + ldsw + _i * 8192), 16, 0, 0); } while (0)
; #define PG8_LDA(dst, b, h) do { _Pragma("unroll") for (int m = 0; m < 4; ++m) _Pragma("unroll") for (int k = 0; k < 2; ++k) dst[m][k] = *(const PG8_LAS bf16x8*)(lds + PG8_SA(b, h) + aoff + m * 2048 + k * 1024); } while (0)
; #define PG8_LDB(dst, b, h) do { _Pragma("unroll") for (int n = 0; n < 2; ++n) _Pragma("unroll") for (int k = 0; k < 2; ++k) dst[n][k] = *(const PG8_LAS bf16x8*)(lds + PG8_SB(b, h) + boff + n * 2048 + k * 1024); } while (0)
; #define PG8_MMA(ai, bj, At, Bt) do { __builtin_amdgcn_s_setprio(1); _Pragma("unroll") for (int m = 0; m < 4; ++m) _Pragma("unroll") for (int n = 0; n < 2; ++n) _Pragma("unroll") for (int k = 0; k < 2; ++k) \
;         acc[ai][bj][m][n] = __builtin_amdgcn_mfma_f32_16x16x32_bf16(Bt[n][k], At[m][k], acc[ai][bj][m][n], 0, 0, 0); __builtin_amdgcn_s_setprio(0); } while (0)
; #define PG8_WAIT_V(n) asm volatile("s_waitcnt vmcnt(" #n ")" ::: "memory")
; #define PG8_WAIT_L(n) asm volatile("s_waitcnt lgkmcnt(" #n ")" ::: "memory")
; #define PG8_BAR __builtin_amdgcn_s_barrier()
; #define PG8_SCHED __builtin_amdgcn_sched_barrier(0)
; template <class Epi, class Sched, bool ALIGN_EPI = false, bool SP2 = false>
; __device__ __forceinline__ void gemm_phase(PG8_LAS unsigned char* lds, const Gemm g, const Sched& S, const Epi& E) {
;     ...
;             PG8_LDB(B0, 0, 0); PG8_LDB(B1, 0, 1); PG8_SCHED; PG8_LDA(At, 0, 0); PG8_STAGE(PG8_SA(1, 1), a1 + hstepA, voffA);
;             PG8_WAIT_V(8); PG8_WAIT_L(0); PG8_BAR; PG8_MMA(0, 0, At, B0); PG8_MMA(0, 1, At, B1); PG8_BAR; PG8_SCHED;
;             PG8_LDA(At, 0, 1); PG8_STAGE(PG8_SB(0, 0), b2, voffB); PG8_STAGE(PG8_SB(0, 1), b2 + hstepB, voffB); PG8_STAGE(PG8_SA(0, 0), a2, voffA);
;             PG8_WAIT_V(8); PG8_WAIT_L(0); PG8_BAR; PG8_MMA(1, 0, At, B0); PG8_MMA(1, 1, At, B1); PG8_BAR; PG8_SCHED;
;     ...
;                     for (int n = 0; n < 2; ++n) acc[a][b][m][n] = (f32x4){0.f, 0.f, 0.f, 0.f};
.Lpeel_p7:
	ds_read_b128 v[144:147], v151
	ds_read_b128 v[154:157], v151 offset:1024
	ds_read_b128 v[158:161], v151 offset:2048
	ds_read_b128 v[162:165], v151 offset:3072
	ds_read_b128 v[166:169], v152
	ds_read_b128 v[170:173], v152 offset:1024
	ds_read_b128 v[176:179], v152 offset:2048
	ds_read_b128 v[180:183], v152 offset:3072
	s_add_u32 s33, s38, 0xfffc0080
	s_addc_u32 s40, s39, -1
	s_cmp_eq_u32 s56, 12
	s_cselect_b32 s43, s13, s40
	s_cselect_b32 s42, s52, s33
	s_cselect_b32 s41, s11, s55
	s_cselect_b32 s40, s53, s54
	ds_read_b128 v[184:187], v153
	ds_read_b128 v[188:191], v153 offset:1024
	ds_read_b128 v[192:195], v153 offset:2048
	ds_read_b128 v[196:199], v153 offset:3072
	ds_read_b128 v[200:203], v153 offset:4096
	ds_read_b128 v[204:207], v153 offset:5120
	ds_read_b128 v[208:211], v153 offset:6144
	ds_read_b128 v[212:215], v153 offset:7168
	s_waitcnt vmcnt(16)
	s_waitcnt lgkmcnt(0)
	s_barrier
	s_setprio 1
	s_waitcnt lgkmcnt(0)
	v_mfma_f32_16x16x32_bf16 v[124:127], v[144:147], v[184:187], 0
	v_mfma_f32_16x16x32_bf16 v[120:123], v[158:161], v[184:187], 0
	v_mfma_f32_16x16x32_bf16 v[108:111], v[144:147], v[192:195], 0
	v_mfma_f32_16x16x32_bf16 v[104:107], v[158:161], v[192:195], 0
	v_mfma_f32_16x16x32_bf16 v[92:95], v[144:147], v[200:203], 0
	v_mfma_f32_16x16x32_bf16 v[88:91], v[158:161], v[200:203], 0
	v_mfma_f32_16x16x32_bf16 v[76:79], v[144:147], v[208:211], 0
	v_mfma_f32_16x16x32_bf16 v[72:75], v[158:161], v[208:211], 0
	v_mfma_f32_16x16x32_bf16 v[124:127], v[154:157], v[188:191], v[124:127]
	v_mfma_f32_16x16x32_bf16 v[120:123], v[162:165], v[188:191], v[120:123]
	v_mfma_f32_16x16x32_bf16 v[108:111], v[154:157], v[196:199], v[108:111]
	v_mfma_f32_16x16x32_bf16 v[104:107], v[162:165], v[196:199], v[104:107]
	v_mfma_f32_16x16x32_bf16 v[92:95], v[154:157], v[204:207], v[92:95]
	v_mfma_f32_16x16x32_bf16 v[88:91], v[162:165], v[204:207], v[88:91]
	v_mfma_f32_16x16x32_bf16 v[76:79], v[154:157], v[212:215], v[76:79]
	v_mfma_f32_16x16x32_bf16 v[72:75], v[162:165], v[212:215], v[72:75]
	s_setprio 0
	s_setprio 1
	v_mfma_f32_16x16x32_bf16 v[116:119], v[166:169], v[184:187], 0
	v_mfma_f32_16x16x32_bf16 v[112:115], v[176:179], v[184:187], 0
	v_mfma_f32_16x16x32_bf16 v[100:103], v[166:169], v[192:195], 0
	v_mfma_f32_16x16x32_bf16 v[96:99], v[176:179], v[192:195], 0
	v_mfma_f32_16x16x32_bf16 v[84:87], v[166:169], v[200:203], 0
	v_mfma_f32_16x16x32_bf16 v[80:83], v[176:179], v[200:203], 0
	v_mfma_f32_16x16x32_bf16 v[68:71], v[166:169], v[208:211], 0
	v_mfma_f32_16x16x32_bf16 v[64:67], v[176:179], v[208:211], 0
	v_mfma_f32_16x16x32_bf16 v[116:119], v[170:173], v[188:191], v[116:119]
	v_mfma_f32_16x16x32_bf16 v[112:115], v[180:183], v[188:191], v[112:115]
	v_mfma_f32_16x16x32_bf16 v[100:103], v[170:173], v[196:199], v[100:103]
	v_mfma_f32_16x16x32_bf16 v[96:99], v[180:183], v[196:199], v[96:99]
	v_mfma_f32_16x16x32_bf16 v[84:87], v[170:173], v[204:207], v[84:87]
	v_mfma_f32_16x16x32_bf16 v[80:83], v[180:183], v[204:207], v[80:83]
	v_mfma_f32_16x16x32_bf16 v[68:71], v[170:173], v[212:215], v[68:71]
	v_mfma_f32_16x16x32_bf16 v[64:67], v[180:183], v[212:215], v[64:67]
	s_setprio 0
	s_barrier
	s_add_i32 s33, s48, s22
	v_lshl_add_u64 v[216:217], s[40:41], 0, v[132:133]
	s_mov_b32 m0, s33
	global_load_lds_dwordx4 v[216:217], off
	s_add_i32 m0, s33, 0x2000
	s_add_u32 s58, s40, 0x40000
	v_lshl_add_u64 v[218:219], s[40:41], 0, v[128:129]
	s_addc_u32 s59, s41, 0
	s_add_i32 s33, s49, s22
	global_load_lds_dwordx4 v[218:219], off
	v_lshl_add_u64 v[220:221], s[58:59], 0, v[132:133]
	s_mov_b32 m0, s33
	v_lshl_add_u64 v[222:223], s[42:43], 0, v[130:131]
	global_load_lds_dwordx4 v[220:221], off
	v_lshl_add_u64 v[220:221], s[58:59], 0, v[128:129]
	s_add_i32 m0, s33, 0x2000
	s_nop 0
	global_load_lds_dwordx4 v[220:221], off
	v_lshl_add_u64 v[220:221], s[42:43], 0, v[134:135]
	s_mov_b32 m0, s29
	s_nop 0
	global_load_lds_dwordx4 v[220:221], off
	s_mov_b32 m0, s30
	s_nop 0
	global_load_lds_dwordx4 v[222:223], off
	ds_read_b128 v[184:187], v153 offset:16384
	ds_read_b128 v[188:191], v153 offset:17408
	ds_read_b128 v[192:195], v153 offset:18432
	ds_read_b128 v[196:199], v153 offset:19456
	ds_read_b128 v[200:203], v153 offset:20480
	ds_read_b128 v[204:207], v153 offset:21504
	ds_read_b128 v[208:211], v153 offset:22528
	ds_read_b128 v[212:215], v153 offset:23552
	s_waitcnt vmcnt(16)
	s_waitcnt lgkmcnt(0)
	s_barrier
	s_setprio 1
	s_waitcnt lgkmcnt(0)
	v_mfma_f32_16x16x32_bf16 v[60:63], v[144:147], v[184:187], 0
	v_mfma_f32_16x16x32_bf16 v[56:59], v[158:161], v[184:187], 0
	v_mfma_f32_16x16x32_bf16 v[44:47], v[144:147], v[192:195], 0
	v_mfma_f32_16x16x32_bf16 v[40:43], v[158:161], v[192:195], 0
	v_mfma_f32_16x16x32_bf16 v[28:31], v[144:147], v[200:203], 0
	v_mfma_f32_16x16x32_bf16 v[24:27], v[158:161], v[200:203], 0
	v_mfma_f32_16x16x32_bf16 v[12:15], v[144:147], v[208:211], 0
	v_mfma_f32_16x16x32_bf16 v[8:11], v[158:161], v[208:211], 0
	v_mfma_f32_16x16x32_bf16 v[60:63], v[154:157], v[188:191], v[60:63]
	v_mfma_f32_16x16x32_bf16 v[56:59], v[162:165], v[188:191], v[56:59]
	v_mfma_f32_16x16x32_bf16 v[44:47], v[154:157], v[196:199], v[44:47]
	v_mfma_f32_16x16x32_bf16 v[40:43], v[162:165], v[196:199], v[40:43]
	v_mfma_f32_16x16x32_bf16 v[28:31], v[154:157], v[204:207], v[28:31]
	v_mfma_f32_16x16x32_bf16 v[24:27], v[162:165], v[204:207], v[24:27]
	v_mfma_f32_16x16x32_bf16 v[12:15], v[154:157], v[212:215], v[12:15]
	v_mfma_f32_16x16x32_bf16 v[8:11], v[162:165], v[212:215], v[8:11]
	s_setprio 0
	s_setprio 1
	v_mfma_f32_16x16x32_bf16 v[52:55], v[166:169], v[184:187], 0
	v_mfma_f32_16x16x32_bf16 v[48:51], v[176:179], v[184:187], 0
	v_mfma_f32_16x16x32_bf16 v[36:39], v[166:169], v[192:195], 0
	v_mfma_f32_16x16x32_bf16 v[32:35], v[176:179], v[192:195], 0
	v_mfma_f32_16x16x32_bf16 v[20:23], v[166:169], v[200:203], 0
	v_mfma_f32_16x16x32_bf16 v[16:19], v[176:179], v[200:203], 0
	v_mfma_f32_16x16x32_bf16 v[4:7], v[166:169], v[208:211], 0
	v_mfma_f32_16x16x32_bf16 v[0:3], v[176:179], v[208:211], 0
	v_mfma_f32_16x16x32_bf16 v[52:55], v[170:173], v[188:191], v[52:55]
	v_mfma_f32_16x16x32_bf16 v[48:51], v[180:183], v[188:191], v[48:51]
	v_mfma_f32_16x16x32_bf16 v[36:39], v[170:173], v[196:199], v[36:39]
	v_mfma_f32_16x16x32_bf16 v[32:35], v[180:183], v[196:199], v[32:35]
	v_mfma_f32_16x16x32_bf16 v[20:23], v[170:173], v[204:207], v[20:23]
	v_mfma_f32_16x16x32_bf16 v[16:19], v[180:183], v[204:207], v[16:19]
	v_mfma_f32_16x16x32_bf16 v[4:7], v[170:173], v[212:215], v[4:7]
	v_mfma_f32_16x16x32_bf16 v[0:3], v[180:183], v[212:215], v[0:3]
	s_setprio 0
	s_barrier
; #define PG8_STAGE(bufoff, gbase, voff) do { _Pragma("unroll") for (int _i = 0; _i < 2; ++_i) \
;         __builtin_amdgcn_global_load_lds((const unsigned*)((const char*)(gbase) + (voff)[_i]), (PG8_LAS unsigned*)(lds + (bufoff) + ldsw + _i * 8192), 16, 0, 0); } while (0)
; #define PG8_LDA(dst, b, h) do { _Pragma("unroll") for (int m = 0; m < 4; ++m) _Pragma("unroll") for (int k = 0; k < 2; ++k) dst[m][k] = *(const PG8_LAS bf16x8*)(lds + PG8_SA(b, h) + aoff + m * 2048 + k * 1024); } while (0)
; #define PG8_LDB(dst, b, h) do { _Pragma("unroll") for (int n = 0; n < 2; ++n) _Pragma("unroll") for (int k = 0; k < 2; ++k) dst[n][k] = *(const PG8_LAS bf16x8*)(lds + PG8_SB(b, h) + boff + n * 2048 + k * 1024); } while (0)
; #define PG8_MMA(ai, bj, At, Bt) do { __builtin_amdgcn_s_setprio(1); _Pragma("unroll") for (int m = 0; m < 4; ++m) _Pragma("unroll") for (int n = 0; n < 2; ++n) _Pragma("unroll") for (int k = 0; k < 2; ++k) \
;         acc[ai][bj][m][n] = __builtin_amdgcn_mfma_f32_16x16x32_bf16(Bt[n][k], At[m][k], acc[ai][bj][m][n], 0, 0, 0); __builtin_amdgcn_s_setprio(0); } while (0)
; #define PG8_WAIT_V(n) asm volatile("s_waitcnt vmcnt(" #n ")" ::: "memory")
; #define PG8_WAIT_L(n) asm volatile("s_waitcnt lgkmcnt(" #n ")" ::: "memory")
; #define PG8_BAR __builtin_amdgcn_s_barrier()
; #define PG8_SCHED __builtin_amdgcn_sched_barrier(0)
; template <class Epi, class Sched, bool ALIGN_EPI = false, bool SP2 = false>
; __device__ __forceinline__ void gemm_phase(PG8_LAS unsigned char* lds, const Gemm g, const Sched& S, const Epi& E) {
;     ...
;             PG8_LDB(B0, 1, 0); PG8_LDB(B1, 1, 1); PG8_SCHED; PG8_LDA(At, 1, 0); PG8_STAGE(PG8_SA(0, 1), a2 + hstepA, voffA);
;             PG8_WAIT_V(8); PG8_WAIT_L(0); PG8_BAR; PG8_MMA(0, 0, At, B0); PG8_MMA(0, 1, At, B1); PG8_BAR; PG8_SCHED;
	s_add_i32 s33, 0, 0x18000
	s_add_i32 s57, 0, 0x1c000
	v_add_u32_e32 v162, s33, v149
	v_add_u32_e32 v175, s57, v149
	s_add_u32 s42, s42, 0x40000
	s_addc_u32 s43, s43, 0
	s_mov_b32 m0, s31
	v_lshl_add_u64 v[224:225], s[42:43], 0, v[134:135]
	global_load_lds_dwordx4 v[224:225], off
	v_lshl_add_u64 v[224:225], s[42:43], 0, v[130:131]
	s_mov_b32 m0, s35
	s_nop 0
	global_load_lds_dwordx4 v[224:225], off
	ds_read_b128 v[144:147], v162
	ds_read_b128 v[154:157], v162 offset:1024
	ds_read_b128 v[158:161], v162 offset:2048
	ds_read_b128 v[162:165], v162 offset:3072
	ds_read_b128 v[166:169], v175
	ds_read_b128 v[170:173], v175 offset:1024
	ds_read_b128 v[176:179], v175 offset:2048
	ds_read_b128 v[180:183], v175 offset:3072
	ds_read_b128 v[184:187], v153 offset:32768
	ds_read_b128 v[188:191], v153 offset:33792
	ds_read_b128 v[192:195], v153 offset:34816
	ds_read_b128 v[196:199], v153 offset:35840
	ds_read_b128 v[200:203], v153 offset:36864
	ds_read_b128 v[204:207], v153 offset:37888
	ds_read_b128 v[208:211], v153 offset:38912
	ds_read_b128 v[212:215], v153 offset:39936
	s_waitcnt vmcnt(16)
	s_waitcnt lgkmcnt(0)
	s_barrier
	s_setprio 1
	s_waitcnt lgkmcnt(0)
	v_mfma_f32_16x16x32_bf16 v[124:127], v[144:147], v[184:187], v[124:127]
	v_mfma_f32_16x16x32_bf16 v[120:123], v[158:161], v[184:187], v[120:123]
	v_mfma_f32_16x16x32_bf16 v[108:111], v[144:147], v[192:195], v[108:111]
	v_mfma_f32_16x16x32_bf16 v[104:107], v[158:161], v[192:195], v[104:107]
	v_mfma_f32_16x16x32_bf16 v[92:95], v[144:147], v[200:203], v[92:95]
	v_mfma_f32_16x16x32_bf16 v[88:91], v[158:161], v[200:203], v[88:91]
	v_mfma_f32_16x16x32_bf16 v[76:79], v[144:147], v[208:211], v[76:79]
	v_mfma_f32_16x16x32_bf16 v[72:75], v[158:161], v[208:211], v[72:75]
	v_mfma_f32_16x16x32_bf16 v[124:127], v[154:157], v[188:191], v[124:127]
	v_mfma_f32_16x16x32_bf16 v[120:123], v[162:165], v[188:191], v[120:123]
	v_mfma_f32_16x16x32_bf16 v[108:111], v[154:157], v[196:199], v[108:111]
	v_mfma_f32_16x16x32_bf16 v[104:107], v[162:165], v[196:199], v[104:107]
	v_mfma_f32_16x16x32_bf16 v[92:95], v[154:157], v[204:207], v[92:95]
	v_mfma_f32_16x16x32_bf16 v[88:91], v[162:165], v[204:207], v[88:91]
	v_mfma_f32_16x16x32_bf16 v[76:79], v[154:157], v[212:215], v[76:79]
	v_mfma_f32_16x16x32_bf16 v[72:75], v[162:165], v[212:215], v[72:75]
	s_setprio 0
	s_setprio 1
	v_mfma_f32_16x16x32_bf16 v[116:119], v[166:169], v[184:187], v[116:119]
	v_mfma_f32_16x16x32_bf16 v[112:115], v[176:179], v[184:187], v[112:115]
	v_mfma_f32_16x16x32_bf16 v[100:103], v[166:169], v[192:195], v[100:103]
	v_mfma_f32_16x16x32_bf16 v[96:99], v[176:179], v[192:195], v[96:99]
	v_mfma_f32_16x16x32_bf16 v[84:87], v[166:169], v[200:203], v[84:87]
	v_mfma_f32_16x16x32_bf16 v[80:83], v[176:179], v[200:203], v[80:83]
	v_mfma_f32_16x16x32_bf16 v[68:71], v[166:169], v[208:211], v[68:71]
	v_mfma_f32_16x16x32_bf16 v[64:67], v[176:179], v[208:211], v[64:67]
	v_mfma_f32_16x16x32_bf16 v[116:119], v[170:173], v[188:191], v[116:119]
	v_mfma_f32_16x16x32_bf16 v[112:115], v[180:183], v[188:191], v[112:115]
	v_mfma_f32_16x16x32_bf16 v[100:103], v[170:173], v[196:199], v[100:103]
	v_mfma_f32_16x16x32_bf16 v[96:99], v[180:183], v[196:199], v[96:99]
	v_mfma_f32_16x16x32_bf16 v[84:87], v[170:173], v[204:207], v[84:87]
	v_mfma_f32_16x16x32_bf16 v[80:83], v[180:183], v[204:207], v[80:83]
	v_mfma_f32_16x16x32_bf16 v[68:71], v[170:173], v[212:215], v[68:71]
	v_mfma_f32_16x16x32_bf16 v[64:67], v[180:183], v[212:215], v[64:67]
	s_setprio 0
	s_barrier
; #define PG8_STAGE(bufoff, gbase, voff) do { _Pragma("unroll") for (int _i = 0; _i < 2; ++_i) \
;         __builtin_amdgcn_global_load_lds((const unsigned*)((const char*)(gbase) + (voff)[_i]), (PG8_LAS unsigned*)(lds + (bufoff) + ldsw + _i * 8192), 16, 0, 0); } while (0)
; #define PG8_LDA(dst, b, h) do { _Pragma("unroll") for (int m = 0; m < 4; ++m) _Pragma("unroll") for (int k = 0; k < 2; ++k) dst[m][k] = *(const PG8_LAS bf16x8*)(lds + PG8_SA(b, h) + aoff + m * 2048 + k * 1024); } while (0)
; #define PG8_MMA(ai, bj, At, Bt) do { __builtin_amdgcn_s_setprio(1); _Pragma("unroll") for (int m = 0; m < 4; ++m) _Pragma("unroll") for (int n = 0; n < 2; ++n) _Pragma("unroll") for (int k = 0; k < 2; ++k) \
;         acc[ai][bj][m][n] = __builtin_amdgcn_mfma_f32_16x16x32_bf16(Bt[n][k], At[m][k], acc[ai][bj][m][n], 0, 0, 0); __builtin_amdgcn_s_setprio(0); } while (0)
; #define PG8_WAIT_V(n) asm volatile("s_waitcnt vmcnt(" #n ")" ::: "memory")
; #define PG8_WAIT_L(n) asm volatile("s_waitcnt lgkmcnt(" #n ")" ::: "memory")
; #define PG8_BAR __builtin_amdgcn_s_barrier()
; #define PG8_SCHED __builtin_amdgcn_sched_barrier(0)
; template <class Epi, class Sched, bool ALIGN_EPI = false, bool SP2 = false>
; __device__ __forceinline__ void gemm_phase(PG8_LAS unsigned char* lds, const Gemm g, const Sched& S, const Epi& E) {
;     ...
;             PG8_LDA(At, 1, 1); PG8_STAGE(PG8_SB(1, 0), b3, voffB); PG8_STAGE(PG8_SB(1, 1), b3 + hstepB, voffB); PG8_STAGE(PG8_SA(1, 0), a3, voffA);
;             PG8_WAIT_V(8); PG8_WAIT_L(0); PG8_BAR; PG8_MMA(1, 0, At, B0); PG8_MMA(1, 1, At, B1); PG8_BAR; PG8_SCHED;
	s_add_i32 s33, s33, s22
	v_lshl_add_u64 v[216:217], v[216:217], 0, s[6:7]
	s_mov_b32 m0, s33
	global_load_lds_dwordx4 v[216:217], off
	s_add_i32 m0, s33, 0x2000
	s_add_u32 s40, s40, 0x40080
	v_lshl_add_u64 v[216:217], v[218:219], 0, s[6:7]
	s_addc_u32 s41, s41, 0
	s_add_i32 s33, s57, s22
	global_load_lds_dwordx4 v[216:217], off
	v_lshl_add_u64 v[216:217], s[40:41], 0, v[132:133]
	s_mov_b32 m0, s33
	s_nop 0
	global_load_lds_dwordx4 v[216:217], off
	v_lshl_add_u64 v[216:217], s[40:41], 0, v[128:129]
	s_add_i32 m0, s33, 0x2000
	s_nop 0
	global_load_lds_dwordx4 v[216:217], off
	v_lshl_add_u64 v[216:217], v[220:221], 0, s[6:7]
	s_mov_b32 m0, s44
	s_nop 0
	global_load_lds_dwordx4 v[216:217], off
	v_lshl_add_u64 v[216:217], v[222:223], 0, s[6:7]
	s_mov_b32 m0, s45
	s_nop 0
	global_load_lds_dwordx4 v[216:217], off
	ds_read_b128 v[184:187], v153 offset:49152
	ds_read_b128 v[188:191], v153 offset:50176
	ds_read_b128 v[192:195], v153 offset:51200
	ds_read_b128 v[196:199], v153 offset:52224
	ds_read_b128 v[200:203], v153 offset:53248
	ds_read_b128 v[204:207], v153 offset:54272
	ds_read_b128 v[208:211], v153 offset:55296
	ds_read_b128 v[212:215], v153 offset:56320
	s_waitcnt vmcnt(8)
	s_waitcnt lgkmcnt(0)
	s_barrier
	s_setprio 1
	s_waitcnt lgkmcnt(0)
	v_mfma_f32_16x16x32_bf16 v[60:63], v[144:147], v[184:187], v[60:63]
	v_mfma_f32_16x16x32_bf16 v[56:59], v[158:161], v[184:187], v[56:59]
	v_mfma_f32_16x16x32_bf16 v[44:47], v[144:147], v[192:195], v[44:47]
	v_mfma_f32_16x16x32_bf16 v[40:43], v[158:161], v[192:195], v[40:43]
	v_mfma_f32_16x16x32_bf16 v[28:31], v[144:147], v[200:203], v[28:31]
	v_mfma_f32_16x16x32_bf16 v[24:27], v[158:161], v[200:203], v[24:27]
	v_mfma_f32_16x16x32_bf16 v[12:15], v[144:147], v[208:211], v[12:15]
	v_mfma_f32_16x16x32_bf16 v[8:11], v[158:161], v[208:211], v[8:11]
	v_mfma_f32_16x16x32_bf16 v[60:63], v[154:157], v[188:191], v[60:63]
	v_mfma_f32_16x16x32_bf16 v[56:59], v[162:165], v[188:191], v[56:59]
	v_mfma_f32_16x16x32_bf16 v[44:47], v[154:157], v[196:199], v[44:47]
	v_mfma_f32_16x16x32_bf16 v[40:43], v[162:165], v[196:199], v[40:43]
	v_mfma_f32_16x16x32_bf16 v[28:31], v[154:157], v[204:207], v[28:31]
	v_mfma_f32_16x16x32_bf16 v[24:27], v[162:165], v[204:207], v[24:27]
	v_mfma_f32_16x16x32_bf16 v[12:15], v[154:157], v[212:215], v[12:15]
	v_mfma_f32_16x16x32_bf16 v[8:11], v[162:165], v[212:215], v[8:11]
	s_setprio 0
	s_setprio 1
	v_mfma_f32_16x16x32_bf16 v[52:55], v[166:169], v[184:187], v[52:55]
	v_mfma_f32_16x16x32_bf16 v[48:51], v[176:179], v[184:187], v[48:51]
	v_mfma_f32_16x16x32_bf16 v[36:39], v[166:169], v[192:195], v[36:39]
	v_mfma_f32_16x16x32_bf16 v[32:35], v[176:179], v[192:195], v[32:35]
	v_mfma_f32_16x16x32_bf16 v[20:23], v[166:169], v[200:203], v[20:23]
	v_mfma_f32_16x16x32_bf16 v[16:19], v[176:179], v[200:203], v[16:19]
	v_mfma_f32_16x16x32_bf16 v[4:7], v[166:169], v[208:211], v[4:7]
	v_mfma_f32_16x16x32_bf16 v[0:3], v[176:179], v[208:211], v[0:3]
	v_mfma_f32_16x16x32_bf16 v[52:55], v[170:173], v[188:191], v[52:55]
	v_mfma_f32_16x16x32_bf16 v[48:51], v[180:183], v[188:191], v[48:51]
	v_mfma_f32_16x16x32_bf16 v[36:39], v[170:173], v[196:199], v[36:39]
	v_mfma_f32_16x16x32_bf16 v[32:35], v[180:183], v[196:199], v[32:35]
	v_mfma_f32_16x16x32_bf16 v[20:23], v[170:173], v[204:207], v[20:23]
	v_mfma_f32_16x16x32_bf16 v[16:19], v[180:183], v[204:207], v[16:19]
	v_mfma_f32_16x16x32_bf16 v[4:7], v[170:173], v[212:215], v[4:7]
	v_mfma_f32_16x16x32_bf16 v[0:3], v[180:183], v[212:215], v[0:3]
	s_setprio 0
	s_barrier
	s_add_i32 s56, s56, 2
	s_add_u32 s38, s38, 0x100
	s_addc_u32 s39, s39, 0
	s_add_u32 s54, s54, 0x100
	s_addc_u32 s55, s55, 0
	s_cmp_gt_u32 s56, 13
	s_branch .LBB0_605
